# in-projection epilogue: the 8 serialized ssq row reductions are preceded by one burst of dummy loads that pulls all their lines into L1 (software prefetch)
# speedup vs baseline: 1.0049x; 1.0049x over previous
; DI float sum16(const float* p) { const f32x4* q = (const f32x4*)p; f32x4 a = q[0], b = q[1], c = q[2], d = q[3]; f32x4 s = (a + b) + (c + d); return (s[0] + s[1]) + (s[2] + s[3]); }
;     template <int PN> DI void body(AccRef acc, const Unit& u, int wr, int wc, int fr, int fq) const {
;     ...
; #pragma unroll
;         for (int ai = 0; ai < 2; ++ai) {
;             const int rb_ = u.pm * 256 + ai * 128 + wr * 64 + fr;
; #pragma unroll
;             for (int m = 0; m < 4; ++m) rinvh[ai][m] = rsqrtf(sum16(ssq + (size_t)(rb_ + 16 * m + zdep) * 16) * (1.f / 1024.f) + EPS);
;             asm volatile("v_mov_b32 %0, 0" : "=v"(zdep) : "v"(rinvh[ai][0]), "v"(rinvh[ai][1]), "v"(rinvh[ai][2]), "v"(rinvh[ai][3]));
;         }
;     DI void operator()(AccRef acc, const Unit& u, int wr, int wc, int fr, int fq) const {
;         switch (u.pn) {
;             case 0: body<0>(acc, u, wr, wc, fr, fq); break;
;             case 1: body<1>(acc, u, wr, wc, fr, fq); break;
;             case 2: body<2>(acc, u, wr, wc, fr, fq); break;
;             case 3: body<3>(acc, u, wr, wc, fr, fq); break;
;             case 4: body<4>(acc, u, wr, wc, fr, fq); break;
;             case 5: body<5>(acc, u, wr, wc, fr, fq); break;
;             case 6: body<6>(acc, u, wr, wc, fr, fq); break;
;             case 7: body<7>(acc, u, wr, wc, fr, fq); break;
;             case 8: body<8>(acc, u, wr, wc, fr, fq); break;
;             default: body<9>(acc, u, wr, wc, fr, fq); break;
.LBB0_353:
	s_mov_b32 s2, s21
	v_mbcnt_lo_u32_b32 v128, -1, 0
	v_mbcnt_hi_u32_b32 v128, -1, v128
	s_mov_b32 s66, s36
	v_and_b32_e32 v214, 15, v128
	v_bfe_u32 v213, v128, 4, 2
	s_lshl_b32 s98, s27, 6
	s_lshl_b32 s99, s34, 8
	s_add_i32 s98, s98, s99
	v_add_u32_e32 v248, s98, v214
	v_lshlrev_b32_e32 v248, 6, v248
	v_lshl_add_u32 v248, v213, 4, v248
	global_load_dwordx4 v[244:247], v248, s[56:57]
	global_load_dwordx4 v[244:247], v248, s[56:57] offset:1024
	global_load_dwordx4 v[244:247], v248, s[56:57] offset:2048
	global_load_dwordx4 v[244:247], v248, s[56:57] offset:3072
	v_add_u32_e32 v248, 0x2000, v248
	global_load_dwordx4 v[244:247], v248, s[56:57]
	global_load_dwordx4 v[244:247], v248, s[56:57] offset:1024
	global_load_dwordx4 v[244:247], v248, s[56:57] offset:2048
	global_load_dwordx4 v[244:247], v248, s[56:57] offset:3072
	s_mov_b32 s53, s27
	s_mov_b64 s[2:3], -1
	s_mov_b64 s[8:9], 0
	s_cmp_lt_i32 s52, 4
	s_mov_b64 s[94:95], 0
	s_cbranch_scc1 .LBB0_372
	s_cmp_gt_i32 s52, 5
	s_cbranch_scc0 .LBB0_366
	s_cmp_gt_i32 s52, 6
	s_cbranch_scc0 .LBB0_363
	s_cmp_gt_i32 s52, 7
	s_cbranch_scc0 .LBB0_360
	s_cmp_eq_u32 s52, 8
	s_mov_b64 s[94:95], -1
	s_cbranch_scc0 .LBB0_359
	s_lshl_b32 s2, s53, 6
	s_lshl_b32 s3, s34, 8
	s_add_i32 s2, s2, s3
	v_add_u32_e32 v160, s2, v214
	v_ashrrev_i32_e32 v161, 31, v160
	v_lshlrev_b64 v[128:129], 6, v[160:161]
	v_lshl_add_u64 v[140:141], s[56:57], 0, v[128:129]
	global_load_dwordx4 v[128:131], v[140:141], off offset:32
	global_load_dwordx4 v[132:135], v[140:141], off offset:48
	global_load_dwordx4 v[136:139], v[140:141], off
	s_nop 0
	global_load_dwordx4 v[140:143], v[140:141], off offset:16
	v_add_u32_e32 v168, 16, v160
	v_ashrrev_i32_e32 v169, 31, v168
	s_mov_b32 s2, 0x358637bd
	s_mov_b32 s4, 0x3a800000
	v_add_u32_e32 v164, 32, v160
	v_ashrrev_i32_e32 v165, 31, v164
	v_add_u32_e32 v166, 48, v160
	v_ashrrev_i32_e32 v167, 31, v166
	v_add_u32_e32 v163, 0x80, v160
	v_add_u32_e32 v173, 0xffffc000, v160
	s_movk_i32 s6, 0x4000
	s_mov_b64 s[12:13], 0x126000
	v_add_u32_e32 v171, 0xffffc080, v160
	v_mov_b32_e32 v175, 0x6800000
	s_mov_b64 s[94:95], 0
	s_waitcnt vmcnt(0)
	v_pk_add_f32 v[130:131], v[130:131], v[134:135]
	v_pk_add_f32 v[128:129], v[128:129], v[132:133]
	v_pk_add_f32 v[138:139], v[138:139], v[142:143]
	v_pk_add_f32 v[136:137], v[136:137], v[140:141]
	v_pk_add_f32 v[130:131], v[138:139], v[130:131]
	v_pk_add_f32 v[128:129], v[136:137], v[128:129]
	s_nop 0
	v_pk_mov_b32 v[132:133], v[128:129], v[130:131] op_sel:[1,0]
	v_mov_b32_e32 v129, v131
	v_pk_add_f32 v[144:145], v[132:133], v[128:129]
	v_lshlrev_b64 v[128:129], 6, v[168:169]
	v_lshl_add_u64 v[140:141], s[56:57], 0, v[128:129]
	global_load_dwordx4 v[128:131], v[140:141], off offset:32
	global_load_dwordx4 v[132:135], v[140:141], off offset:48
	global_load_dwordx4 v[136:139], v[140:141], off
	s_nop 0
	global_load_dwordx4 v[140:143], v[140:141], off offset:16
	s_waitcnt vmcnt(2)
	v_pk_add_f32 v[130:131], v[130:131], v[134:135]
	v_pk_add_f32 v[128:129], v[128:129], v[132:133]
	s_waitcnt vmcnt(0)
	v_pk_add_f32 v[138:139], v[138:139], v[142:143]
	v_pk_add_f32 v[136:137], v[136:137], v[140:141]
	v_pk_add_f32 v[130:131], v[138:139], v[130:131]
	v_pk_add_f32 v[128:129], v[136:137], v[128:129]
	s_nop 0
	v_pk_mov_b32 v[132:133], v[128:129], v[130:131] op_sel:[1,0]
	v_mov_b32_e32 v129, v131
	v_pk_add_f32 v[128:129], v[132:133], v[128:129]
	v_mov_b32_e32 v131, v144
	v_mov_b32_e32 v130, v128
	v_mov_b32_e32 v144, v129
	v_pk_add_f32 v[130:131], v[130:131], v[144:145]
	v_mov_b64_e32 v[128:129], s[2:3]
	v_pk_fma_f32 v[130:131], v[130:131], s[4:5], v[128:129] op_sel_hi:[1,0,0]
	s_nop 0
	v_mul_f32_e32 v132, 0x4b800000, v131
	v_cmp_gt_f32_e64 s[2:3], s33, v131
	v_cmp_gt_f32_e32 vcc, s33, v130
	s_nop 0
	v_cndmask_b32_e64 v131, v131, v132, s[2:3]
	v_rsq_f32_e32 v131, v131
	s_nop 0
	v_mul_f32_e32 v132, 0x45800000, v131
	v_cndmask_b32_e64 v188, v131, v132, s[2:3]
	v_mul_f32_e32 v131, 0x4b800000, v130
	v_cndmask_b32_e32 v130, v130, v131, vcc
	v_rsq_f32_e32 v130, v130
	s_nop 0
	v_mul_f32_e32 v131, 0x45800000, v130
	v_cndmask_b32_e32 v162, v130, v131, vcc
	v_lshlrev_b64 v[130:131], 6, v[164:165]
	v_lshl_add_u64 v[142:143], s[56:57], 0, v[130:131]
	global_load_dwordx4 v[130:133], v[142:143], off offset:32
	global_load_dwordx4 v[134:137], v[142:143], off offset:48
	global_load_dwordx4 v[138:141], v[142:143], off
	s_nop 0
	global_load_dwordx4 v[142:145], v[142:143], off offset:16
	s_waitcnt vmcnt(2)
	v_pk_add_f32 v[132:133], v[132:133], v[136:137]
	v_pk_add_f32 v[130:131], v[130:131], v[134:135]
	s_waitcnt vmcnt(0)
	v_pk_add_f32 v[140:141], v[140:141], v[144:145]
	v_pk_add_f32 v[138:139], v[138:139], v[142:143]
	v_pk_add_f32 v[132:133], v[140:141], v[132:133]
	v_pk_add_f32 v[130:131], v[138:139], v[130:131]
	s_nop 0
	v_pk_mov_b32 v[134:135], v[130:131], v[132:133] op_sel:[1,0]
	v_mov_b32_e32 v131, v133
	v_pk_add_f32 v[146:147], v[134:135], v[130:131]
	v_lshlrev_b64 v[130:131], 6, v[166:167]
	v_lshl_add_u64 v[142:143], s[56:57], 0, v[130:131]
	global_load_dwordx4 v[130:133], v[142:143], off offset:32
	global_load_dwordx4 v[134:137], v[142:143], off offset:48
	global_load_dwordx4 v[138:141], v[142:143], off
	s_nop 0
	global_load_dwordx4 v[142:145], v[142:143], off offset:16
	s_waitcnt vmcnt(2)
	v_pk_add_f32 v[132:133], v[132:133], v[136:137]
	v_pk_add_f32 v[130:131], v[130:131], v[134:135]
	s_waitcnt vmcnt(0)
; DI float sum16(const float* p) { const f32x4* q = (const f32x4*)p; f32x4 a = q[0], b = q[1], c = q[2], d = q[3]; f32x4 s = (a + b) + (c + d); return (s[0] + s[1]) + (s[2] + s[3]); }
;     template <int PN> DI void body(AccRef acc, const Unit& u, int wr, int wc, int fr, int fq) const {
;     ...
; #pragma unroll
;         for (int ai = 0; ai < 2; ++ai) {
;             const int rb_ = u.pm * 256 + ai * 128 + wr * 64 + fr;
; #pragma unroll
;             for (int m = 0; m < 4; ++m) rinvh[ai][m] = rsqrtf(sum16(ssq + (size_t)(rb_ + 16 * m + zdep) * 16) * (1.f / 1024.f) + EPS);
;             asm volatile("v_mov_b32 %0, 0" : "=v"(zdep) : "v"(rinvh[ai][0]), "v"(rinvh[ai][1]), "v"(rinvh[ai][2]), "v"(rinvh[ai][3]));
;         }
	v_pk_add_f32 v[140:141], v[140:141], v[144:145]
	v_pk_add_f32 v[138:139], v[138:139], v[142:143]
	v_pk_add_f32 v[132:133], v[140:141], v[132:133]
	v_pk_add_f32 v[130:131], v[138:139], v[130:131]
	s_nop 0
	v_pk_mov_b32 v[134:135], v[130:131], v[132:133] op_sel:[1,0]
	v_mov_b32_e32 v131, v133
	v_pk_add_f32 v[130:131], v[134:135], v[130:131]
	v_mov_b32_e32 v133, v146
	v_mov_b32_e32 v132, v130
	v_mov_b32_e32 v146, v131
	v_pk_add_f32 v[130:131], v[132:133], v[146:147]
	s_nop 0
	v_pk_fma_f32 v[130:131], v[130:131], s[4:5], v[128:129] op_sel_hi:[1,0,0]
	s_nop 0
	v_mul_f32_e32 v132, 0x4b800000, v131
	v_cmp_gt_f32_e64 s[2:3], s33, v131
	v_cmp_gt_f32_e32 vcc, s33, v130
	s_nop 0
	v_cndmask_b32_e64 v131, v131, v132, s[2:3]
	v_rsq_f32_e32 v131, v131
	s_nop 0
	v_mul_f32_e32 v132, 0x45800000, v131
	v_cndmask_b32_e64 v170, v131, v132, s[2:3]
	v_mul_f32_e32 v131, 0x4b800000, v130
	v_cndmask_b32_e32 v130, v130, v131, vcc
	v_rsq_f32_e32 v130, v130
	s_nop 0
	v_mul_f32_e32 v131, 0x45800000, v130
	v_cndmask_b32_e32 v174, v130, v131, vcc
	v_mov_b32 v130, 0
	s_nop 0
	v_add_u32_e32 v130, v130, v163
	v_ashrrev_i32_e32 v131, 31, v130
	v_lshlrev_b64 v[132:133], 6, v[130:131]
	v_lshl_add_u64 v[144:145], s[56:57], 0, v[132:133]
	global_load_dwordx4 v[132:135], v[144:145], off offset:32
	global_load_dwordx4 v[136:139], v[144:145], off offset:48
	global_load_dwordx4 v[140:143], v[144:145], off
	s_nop 0
	global_load_dwordx4 v[144:147], v[144:145], off offset:16
	s_waitcnt vmcnt(2)
	v_pk_add_f32 v[134:135], v[134:135], v[138:139]
	v_pk_add_f32 v[132:133], v[132:133], v[136:137]
	s_waitcnt vmcnt(0)
	v_pk_add_f32 v[142:143], v[142:143], v[146:147]
	v_pk_add_f32 v[140:141], v[140:141], v[144:145]
	v_pk_add_f32 v[134:135], v[142:143], v[134:135]
	v_pk_add_f32 v[132:133], v[140:141], v[132:133]
	s_nop 0
	v_pk_mov_b32 v[136:137], v[132:133], v[134:135] op_sel:[1,0]
	v_mov_b32_e32 v133, v135
	v_pk_add_f32 v[148:149], v[136:137], v[132:133]
	v_add_u32_e32 v132, 16, v130
	v_ashrrev_i32_e32 v133, 31, v132
	v_lshlrev_b64 v[132:133], 6, v[132:133]
	v_lshl_add_u64 v[144:145], s[56:57], 0, v[132:133]
	global_load_dwordx4 v[132:135], v[144:145], off offset:32
	global_load_dwordx4 v[136:139], v[144:145], off offset:48
	global_load_dwordx4 v[140:143], v[144:145], off
	s_nop 0
	global_load_dwordx4 v[144:147], v[144:145], off offset:16
	s_waitcnt vmcnt(2)
	v_pk_add_f32 v[134:135], v[134:135], v[138:139]
	v_pk_add_f32 v[132:133], v[132:133], v[136:137]
	s_waitcnt vmcnt(0)
	v_pk_add_f32 v[142:143], v[142:143], v[146:147]
	v_pk_add_f32 v[140:141], v[140:141], v[144:145]
	v_pk_add_f32 v[134:135], v[142:143], v[134:135]
	v_pk_add_f32 v[132:133], v[140:141], v[132:133]
	s_nop 0
	v_pk_mov_b32 v[136:137], v[132:133], v[134:135] op_sel:[1,0]
	v_mov_b32_e32 v133, v135
	v_pk_add_f32 v[132:133], v[136:137], v[132:133]
	v_mov_b32_e32 v135, v148
	v_mov_b32_e32 v134, v132
	v_mov_b32_e32 v148, v133
	v_pk_add_f32 v[132:133], v[134:135], v[148:149]
	s_nop 0
	v_pk_fma_f32 v[132:133], v[132:133], s[4:5], v[128:129] op_sel_hi:[1,0,0]
	s_nop 0
	v_mul_f32_e32 v131, 0x4b800000, v133
	v_cmp_gt_f32_e64 s[2:3], s33, v133
	v_cmp_gt_f32_e32 vcc, s33, v132
	s_nop 0
	v_cndmask_b32_e64 v131, v133, v131, s[2:3]
	v_rsq_f32_e32 v131, v131
	s_nop 0
	v_mul_f32_e32 v133, 0x45800000, v131
	v_cndmask_b32_e64 v190, v131, v133, s[2:3]
	v_mul_f32_e32 v131, 0x4b800000, v132
	v_cndmask_b32_e32 v131, v132, v131, vcc
	v_rsq_f32_e32 v131, v131
	s_nop 0
	v_mul_f32_e32 v132, 0x45800000, v131
	v_cndmask_b32_e32 v172, v131, v132, vcc
	v_add_u32_e32 v132, 32, v130
	v_ashrrev_i32_e32 v133, 31, v132
	v_lshlrev_b64 v[132:133], 6, v[132:133]
	v_lshl_add_u64 v[144:145], s[56:57], 0, v[132:133]
	global_load_dwordx4 v[132:135], v[144:145], off offset:32
	global_load_dwordx4 v[136:139], v[144:145], off offset:48
	global_load_dwordx4 v[140:143], v[144:145], off
	s_nop 0
	global_load_dwordx4 v[144:147], v[144:145], off offset:16
	v_add_u32_e32 v130, 48, v130
	v_ashrrev_i32_e32 v131, 31, v130
	v_lshlrev_b64 v[130:131], 6, v[130:131]
	s_waitcnt vmcnt(2)
	v_pk_add_f32 v[134:135], v[134:135], v[138:139]
	v_pk_add_f32 v[132:133], v[132:133], v[136:137]
	s_waitcnt vmcnt(0)
	v_pk_add_f32 v[142:143], v[142:143], v[146:147]
	v_pk_add_f32 v[140:141], v[140:141], v[144:145]
	v_pk_add_f32 v[134:135], v[142:143], v[134:135]
	v_pk_add_f32 v[132:133], v[140:141], v[132:133]
	v_lshl_add_u64 v[142:143], s[56:57], 0, v[130:131]
	v_pk_mov_b32 v[136:137], v[132:133], v[134:135] op_sel:[1,0]
	v_mov_b32_e32 v133, v135
	v_pk_add_f32 v[146:147], v[136:137], v[132:133]
	global_load_dwordx4 v[130:133], v[142:143], off offset:32
	global_load_dwordx4 v[134:137], v[142:143], off offset:48
	global_load_dwordx4 v[138:141], v[142:143], off
	s_nop 0
	global_load_dwordx4 v[142:145], v[142:143], off offset:16
	s_waitcnt vmcnt(2)
	v_pk_add_f32 v[132:133], v[132:133], v[136:137]
	v_pk_add_f32 v[130:131], v[130:131], v[134:135]
	s_waitcnt vmcnt(0)
; DI float sum16(const float* p) { const f32x4* q = (const f32x4*)p; f32x4 a = q[0], b = q[1], c = q[2], d = q[3]; f32x4 s = (a + b) + (c + d); return (s[0] + s[1]) + (s[2] + s[3]); }
;     template <int PN> DI void body(AccRef acc, const Unit& u, int wr, int wc, int fr, int fq) const {
;     ...
;             for (int m = 0; m < 4; ++m) rinvh[ai][m] = rsqrtf(sum16(ssq + (size_t)(rb_ + 16 * m + zdep) * 16) * (1.f / 1024.f) + EPS);
;             asm volatile("v_mov_b32 %0, 0" : "=v"(zdep) : "v"(rinvh[ai][0]), "v"(rinvh[ai][1]), "v"(rinvh[ai][2]), "v"(rinvh[ai][3]));
;         }
; #pragma unroll
;         for (int ai = 0; ai < 2; ++ai) {
;             const int rb_ = u.pm * 256 + ai * 128 + wr * 64 + fr;
;             int mb_, p_, k_; row_info(rb_, mb_, p_, k_);
; #pragma unroll
;             for (int bj = 0; bj < 2; ++bj)
; #pragma unroll
;                 for (int n = 0; n < 2; ++n) cvh[ai][bj][n] = *(const f32x4*)(cv + (size_t)(mb_ + zdep) * NIN + PN * 256 + bj * 128 + cl + 4 * n);
;         }
;     ...
;                     float* lo = orow(out, l, row, PN == 8 ? O_PSK : O_PSV, PN == 8 ? O_SSK : O_SSV, 256);
; #pragma unroll
;                     for (int bj = 0; bj < 2; ++bj) {
;                         *(f32x4*)(lo + bj * 128 + cl) = (f32x4){v[bj][0], v[bj][1], v[bj][2], v[bj][3]};
;                         *(f32x4*)(lo + bj * 128 + cl + 4) = (f32x4){v[bj][4], v[bj][5], v[bj][6], v[bj][7]};
;                     }
	v_pk_add_f32 v[140:141], v[140:141], v[144:145]
	v_pk_add_f32 v[138:139], v[138:139], v[142:143]
	v_pk_add_f32 v[132:133], v[140:141], v[132:133]
	v_pk_add_f32 v[130:131], v[138:139], v[130:131]
	s_nop 0
	v_pk_mov_b32 v[134:135], v[130:131], v[132:133] op_sel:[1,0]
	v_mov_b32_e32 v131, v133
	v_pk_add_f32 v[130:131], v[134:135], v[130:131]
	v_mov_b32_e32 v133, v146
	v_mov_b32_e32 v132, v130
	v_mov_b32_e32 v146, v131
	v_pk_add_f32 v[130:131], v[132:133], v[146:147]
	s_nop 0
	v_pk_fma_f32 v[128:129], v[130:131], s[4:5], v[128:129] op_sel_hi:[1,0,0]
	v_lshrrev_b32_e32 v131, 6, v173
	v_mul_f32_e32 v130, 0x4b800000, v129
	v_cmp_gt_f32_e64 s[2:3], s33, v129
	v_cmp_gt_f32_e32 vcc, s33, v128
	v_add_u32_e32 v131, 8, v131
	v_cndmask_b32_e64 v129, v129, v130, s[2:3]
	v_rsq_f32_e32 v129, v129
	s_nop 0
	v_mul_f32_e32 v130, 0x45800000, v129
	v_cndmask_b32_e64 v192, v129, v130, s[2:3]
	v_mul_f32_e32 v129, 0x4b800000, v128
	v_cndmask_b32_e32 v128, v128, v129, vcc
	v_rsq_f32_e32 v128, v128
	s_lshl_b32 s2, s66, 5
	v_ashrrev_i32_e32 v130, 11, v160
	v_mul_f32_e32 v129, 0x45800000, v128
	v_cndmask_b32_e32 v194, v128, v129, vcc
	v_lshl_add_u32 v128, v213, 3, s2
	v_cmp_gt_i32_e64 s[2:3], s6, v160
	v_mov_b32 v134, 0
	v_ashrrev_i32_e32 v129, 31, v128
	v_lshlrev_b64 v[196:197], 2, v[128:129]
	v_cndmask_b32_e64 v130, v131, v130, s[2:3]
	v_add_u32_e32 v132, v134, v130
	v_mov_b64_e32 v[130:131], s[10:11]
	v_mad_i64_i32 v[132:133], s[4:5], v132, s51, v[130:131]
	v_lshl_add_u64 v[128:129], v[132:133], 0, v[196:197]
	v_lshl_add_u64 v[132:133], v[128:129], 0, s[12:13]
	v_add_co_u32_e32 v128, vcc, s62, v128
	v_cndmask_b32_e64 v198, v173, v160, s[2:3]
	s_nop 0
	v_addc_co_u32_e32 v129, vcc, 0, v129, vcc
	global_load_dwordx4 v[152:155], v[128:129], off
	global_load_dwordx4 v[156:159], v[132:133], off offset:16
	global_load_dwordx4 v[144:147], v[132:133], off offset:528
	global_load_dwordx4 v[148:151], v[132:133], off offset:512
	v_lshrrev_b32_e32 v129, 6, v171
	v_cmp_gt_i32_e32 vcc, s6, v163
	v_ashrrev_i32_e32 v128, 11, v163
	v_add_u32_e32 v129, 8, v129
	v_cndmask_b32_e32 v128, v129, v128, vcc
	v_add_u32_e32 v128, v134, v128
	v_mad_i64_i32 v[128:129], s[4:5], v128, s51, v[130:131]
	v_lshl_add_u64 v[128:129], v[128:129], 0, v[196:197]
	v_lshl_add_u64 v[132:133], v[128:129], 0, s[12:13]
	v_add_co_u32_e64 v128, s[4:5], s62, v128
	v_mov_b32_e32 v173, 0xab98000
	s_nop 0
	v_addc_co_u32_e64 v129, s[4:5], 0, v129, s[4:5]
	global_load_dwordx4 v[140:143], v[128:129], off
	global_load_dwordx4 v[136:139], v[132:133], off offset:16
	s_nop 0
	global_load_dwordx4 v[128:131], v[132:133], off offset:528
	s_nop 0
	global_load_dwordx4 v[132:135], v[132:133], off offset:512
	v_cndmask_b32_e64 v199, 0, v161, s[2:3]
	v_cndmask_b32_e64 v224, v173, v175, s[2:3]
	v_lshl_add_u64 v[200:201], s[42:43], 0, v[224:225]
	v_lshlrev_b64 v[198:199], 10, v[198:199]
	v_lshl_add_u64 v[198:199], v[200:201], 0, v[198:199]
	v_lshl_add_u64 v[202:203], v[198:199], 0, v[196:197]
	v_cmp_gt_i32_e64 s[2:3], s82, v160
	v_add_u32_e32 v161, 0xffffc010, v160
	s_waitcnt vmcnt(7)
	v_pk_fma_f32 v[200:201], v[126:127], v[188:189], v[154:155] op_sel_hi:[1,0,1]
	v_pk_fma_f32 v[198:199], v[124:125], v[188:189], v[152:153] op_sel_hi:[1,0,1]
	global_store_dwordx4 v[202:203], v[198:201], off
	v_cndmask_b32_e64 v169, 0, v169, s[2:3]
	v_cndmask_b32_e64 v168, v161, v168, s[2:3]
	s_waitcnt vmcnt(7)
	v_pk_fma_f32 v[200:201], v[122:123], v[188:189], v[158:159] op_sel_hi:[1,0,1]
	v_pk_fma_f32 v[198:199], v[120:121], v[188:189], v[156:157] op_sel_hi:[1,0,1]
	global_store_dwordx4 v[202:203], v[198:201], off offset:16
	v_cndmask_b32_e64 v224, v173, v175, s[2:3]
	v_lshlrev_b64 v[168:169], 10, v[168:169]
	s_waitcnt vmcnt(6)
	v_pk_fma_f32 v[200:201], v[118:119], v[188:189], v[150:151] op_sel_hi:[1,0,1]
	v_pk_fma_f32 v[198:199], v[116:117], v[188:189], v[148:149] op_sel_hi:[1,0,1]
	global_store_dwordx4 v[202:203], v[198:201], off offset:512
	v_cmp_gt_i32_e64 s[2:3], s83, v160
	v_add_u32_e32 v161, 0xffffc020, v160
	v_pk_fma_f32 v[200:201], v[114:115], v[188:189], v[146:147] op_sel_hi:[1,0,1]
	v_pk_fma_f32 v[198:199], v[112:113], v[188:189], v[144:145] op_sel_hi:[1,0,1]
	v_lshl_add_u64 v[188:189], s[42:43], 0, v[224:225]
	v_lshl_add_u64 v[168:169], v[188:189], 0, v[168:169]
	global_store_dwordx4 v[202:203], v[198:201], off offset:528
	v_lshl_add_u64 v[168:169], v[168:169], 0, v[196:197]
	v_cndmask_b32_e64 v165, 0, v165, s[2:3]
	v_pk_fma_f32 v[200:201], v[110:111], v[162:163], v[154:155] op_sel_hi:[1,0,1]
	v_pk_fma_f32 v[198:199], v[108:109], v[162:163], v[152:153] op_sel_hi:[1,0,1]
	global_store_dwordx4 v[168:169], v[198:201], off
	v_cndmask_b32_e64 v164, v161, v164, s[2:3]
	v_cndmask_b32_e64 v224, v173, v175, s[2:3]
	v_pk_fma_f32 v[200:201], v[106:107], v[162:163], v[158:159] op_sel_hi:[1,0,1]
	v_pk_fma_f32 v[198:199], v[104:105], v[162:163], v[156:157] op_sel_hi:[1,0,1]
	global_store_dwordx4 v[168:169], v[198:201], off offset:16
	v_lshlrev_b64 v[164:165], 10, v[164:165]
	v_cmp_gt_i32_e64 s[2:3], s92, v160
	v_pk_fma_f32 v[200:201], v[102:103], v[162:163], v[150:151] op_sel_hi:[1,0,1]
	v_pk_fma_f32 v[198:199], v[100:101], v[162:163], v[148:149] op_sel_hi:[1,0,1]
	global_store_dwordx4 v[168:169], v[198:201], off offset:512
	v_add_u32_e32 v161, 0xffffc030, v160
	s_nop 0
	v_pk_fma_f32 v[200:201], v[98:99], v[162:163], v[146:147] op_sel_hi:[1,0,1]
	v_pk_fma_f32 v[198:199], v[96:97], v[162:163], v[144:145] op_sel_hi:[1,0,1]
	global_store_dwordx4 v[168:169], v[198:201], off offset:528
	v_lshl_add_u64 v[168:169], s[42:43], 0, v[224:225]
	v_lshl_add_u64 v[164:165], v[168:169], 0, v[164:165]
	v_lshl_add_u64 v[164:165], v[164:165], 0, v[196:197]
;     template <int PN> DI void body(AccRef acc, const Unit& u, int wr, int wc, int fr, int fq) const {
;     ...
;                 const int row = rb + 16 * m, pos = pos0 + 16 * m, kvrow = kv0 + 16 * m;
;                 const float rinv = rinvh[ai][m];
;                 float v[2][8];
; #pragma unroll
;                 for (int bj = 0; bj < 2; ++bj)
; #pragma unroll
;                     for (int n = 0; n < 2; ++n)
; #pragma unroll
;                         for (int j = 0; j < 4; ++j) v[bj][4 * n + j] = acc[ai][bj][m][n][j] * rinv + cvh[ai][bj][n][j];
;     ...
;                     float* lo = orow(out, l, row, PN == 8 ? O_PSK : O_PSV, PN == 8 ? O_SSK : O_SSV, 256);
; #pragma unroll
;                     for (int bj = 0; bj < 2; ++bj) {
;                         *(f32x4*)(lo + bj * 128 + cl) = (f32x4){v[bj][0], v[bj][1], v[bj][2], v[bj][3]};
;                         *(f32x4*)(lo + bj * 128 + cl + 4) = (f32x4){v[bj][4], v[bj][5], v[bj][6], v[bj][7]};
;                     }
	v_pk_fma_f32 v[200:201], v[94:95], v[170:171], v[154:155] op_sel_hi:[1,0,1]
	v_pk_fma_f32 v[198:199], v[92:93], v[170:171], v[152:153] op_sel_hi:[1,0,1]
	global_store_dwordx4 v[164:165], v[198:201], off
	v_cndmask_b32_e64 v224, v173, v175, s[2:3]
	v_pk_fma_f32 v[154:155], v[78:79], v[174:175], v[154:155] op_sel_hi:[1,0,1]
	v_pk_fma_f32 v[200:201], v[90:91], v[170:171], v[158:159] op_sel_hi:[1,0,1]
	v_pk_fma_f32 v[198:199], v[88:89], v[170:171], v[156:157] op_sel_hi:[1,0,1]
	global_store_dwordx4 v[164:165], v[198:201], off offset:16
	v_pk_fma_f32 v[152:153], v[76:77], v[174:175], v[152:153] op_sel_hi:[1,0,1]
	s_nop 0
	v_pk_fma_f32 v[200:201], v[86:87], v[170:171], v[150:151] op_sel_hi:[1,0,1]
	v_pk_fma_f32 v[198:199], v[84:85], v[170:171], v[148:149] op_sel_hi:[1,0,1]
	global_store_dwordx4 v[164:165], v[198:201], off offset:512
	v_pk_fma_f32 v[150:151], v[70:71], v[174:175], v[150:151] op_sel_hi:[1,0,1]
	v_pk_fma_f32 v[148:149], v[68:69], v[174:175], v[148:149] op_sel_hi:[1,0,1]
	v_pk_fma_f32 v[200:201], v[82:83], v[170:171], v[146:147] op_sel_hi:[1,0,1]
	v_pk_fma_f32 v[198:199], v[80:81], v[170:171], v[144:145] op_sel_hi:[1,0,1]
	global_store_dwordx4 v[164:165], v[198:201], off offset:528
	v_cndmask_b32_e64 v165, 0, v167, s[2:3]
	v_cndmask_b32_e64 v164, v161, v166, s[2:3]
	v_lshl_add_u64 v[166:167], s[42:43], 0, v[224:225]
	v_lshlrev_b64 v[164:165], 10, v[164:165]
	v_lshl_add_u64 v[164:165], v[166:167], 0, v[164:165]
	v_lshl_add_u64 v[164:165], v[164:165], 0, v[196:197]
	v_pk_fma_f32 v[146:147], v[66:67], v[174:175], v[146:147] op_sel_hi:[1,0,1]
	v_pk_fma_f32 v[144:145], v[64:65], v[174:175], v[144:145] op_sel_hi:[1,0,1]
	global_store_dwordx4 v[164:165], v[144:147], off offset:528
	v_cndmask_b32_e32 v224, v173, v175, vcc
	global_store_dwordx4 v[164:165], v[152:155], off
	v_ashrrev_i32_e32 v144, 31, v163
	v_cndmask_b32_e32 v145, 0, v144, vcc
	v_cndmask_b32_e32 v144, v171, v163, vcc
	v_lshl_add_u64 v[146:147], s[42:43], 0, v[224:225]
	v_lshlrev_b64 v[144:145], 10, v[144:145]
	v_lshl_add_u64 v[144:145], v[146:147], 0, v[144:145]
	v_pk_fma_f32 v[154:155], v[74:75], v[174:175], v[158:159] op_sel_hi:[1,0,1]
	v_pk_fma_f32 v[152:153], v[72:73], v[174:175], v[156:157] op_sel_hi:[1,0,1]
	global_store_dwordx4 v[164:165], v[148:151], off offset:512
	s_waitcnt vmcnt(18)
	v_pk_fma_f32 v[146:147], v[62:63], v[190:191], v[142:143] op_sel_hi:[1,0,1]
	global_store_dwordx4 v[164:165], v[152:155], off offset:16
	v_lshl_add_u64 v[148:149], v[144:145], 0, v[196:197]
	v_pk_fma_f32 v[144:145], v[60:61], v[190:191], v[140:141] op_sel_hi:[1,0,1]
	global_store_dwordx4 v[148:149], v[144:147], off
	v_cmp_gt_i32_e32 vcc, s82, v163
	s_waitcnt vmcnt(19)
	v_pk_fma_f32 v[146:147], v[58:59], v[190:191], v[138:139] op_sel_hi:[1,0,1]
	v_pk_fma_f32 v[144:145], v[56:57], v[190:191], v[136:137] op_sel_hi:[1,0,1]
	global_store_dwordx4 v[148:149], v[144:147], off offset:16
	v_cndmask_b32_e32 v224, v173, v175, vcc
	s_waitcnt vmcnt(18)
;     template <int PN> DI void body(AccRef acc, const Unit& u, int wr, int wc, int fr, int fq) const {
;     ...
;                     float* lo = orow(out, l, row, PN == 8 ? O_PSK : O_PSV, PN == 8 ? O_SSK : O_SSV, 256);
; #pragma unroll
;                     for (int bj = 0; bj < 2; ++bj) {
;                         *(f32x4*)(lo + bj * 128 + cl) = (f32x4){v[bj][0], v[bj][1], v[bj][2], v[bj][3]};
;                         *(f32x4*)(lo + bj * 128 + cl + 4) = (f32x4){v[bj][4], v[bj][5], v[bj][6], v[bj][7]};
;                     }
	v_pk_fma_f32 v[146:147], v[54:55], v[190:191], v[134:135] op_sel_hi:[1,0,1]
	v_pk_fma_f32 v[144:145], v[52:53], v[190:191], v[132:133] op_sel_hi:[1,0,1]
	global_store_dwordx4 v[148:149], v[144:147], off offset:512
	s_nop 1
	v_pk_fma_f32 v[146:147], v[50:51], v[190:191], v[130:131] op_sel_hi:[1,0,1]
	v_pk_fma_f32 v[144:145], v[48:49], v[190:191], v[128:129] op_sel_hi:[1,0,1]
	global_store_dwordx4 v[148:149], v[144:147], off offset:528
	s_nop 1
	v_add_u32_e32 v146, 0x90, v160
	v_add_u32_e32 v144, 0xffffc090, v160
	v_ashrrev_i32_e32 v145, 31, v146
	v_cndmask_b32_e32 v145, 0, v145, vcc
	v_cndmask_b32_e32 v144, v144, v146, vcc
	v_lshl_add_u64 v[146:147], s[42:43], 0, v[224:225]
	v_lshlrev_b64 v[144:145], 10, v[144:145]
	v_lshl_add_u64 v[144:145], v[146:147], 0, v[144:145]
	v_lshl_add_u64 v[148:149], v[144:145], 0, v[196:197]
	v_pk_fma_f32 v[146:147], v[46:47], v[172:173], v[142:143] op_sel_hi:[1,0,1]
	v_pk_fma_f32 v[144:145], v[44:45], v[172:173], v[140:141] op_sel_hi:[1,0,1]
	global_store_dwordx4 v[148:149], v[144:147], off
	v_cmp_gt_i32_e32 vcc, s83, v163
	s_nop 0
	v_pk_fma_f32 v[146:147], v[42:43], v[172:173], v[138:139] op_sel_hi:[1,0,1]
	v_pk_fma_f32 v[144:145], v[40:41], v[172:173], v[136:137] op_sel_hi:[1,0,1]
	global_store_dwordx4 v[148:149], v[144:147], off offset:16
	v_cndmask_b32_e32 v224, v173, v175, vcc
	s_nop 0
	v_pk_fma_f32 v[146:147], v[38:39], v[172:173], v[134:135] op_sel_hi:[1,0,1]
	v_pk_fma_f32 v[144:145], v[36:37], v[172:173], v[132:133] op_sel_hi:[1,0,1]
	global_store_dwordx4 v[148:149], v[144:147], off offset:512
	s_nop 1
	v_pk_fma_f32 v[146:147], v[30:31], v[172:173], v[130:131] op_sel_hi:[1,0,1]
	v_pk_fma_f32 v[144:145], v[28:29], v[172:173], v[128:129] op_sel_hi:[1,0,1]
	global_store_dwordx4 v[148:149], v[144:147], off offset:528
	s_nop 1
	v_add_u32_e32 v146, 0xa0, v160
	v_add_u32_e32 v144, 0xffffc0a0, v160
	v_ashrrev_i32_e32 v145, 31, v146
	v_cndmask_b32_e32 v145, 0, v145, vcc
	v_cndmask_b32_e32 v144, v144, v146, vcc
	v_lshl_add_u64 v[146:147], s[42:43], 0, v[224:225]
	v_lshlrev_b64 v[144:145], 10, v[144:145]
	v_lshl_add_u64 v[144:145], v[146:147], 0, v[144:145]
	v_lshl_add_u64 v[148:149], v[144:145], 0, v[196:197]
	v_pk_fma_f32 v[146:147], v[34:35], v[192:193], v[142:143] op_sel_hi:[1,0,1]
	v_pk_fma_f32 v[144:145], v[32:33], v[192:193], v[140:141] op_sel_hi:[1,0,1]
	global_store_dwordx4 v[148:149], v[144:147], off
	v_cmp_gt_i32_e32 vcc, s92, v163
	v_pk_fma_f32 v[142:143], v[14:15], v[194:195], v[142:143] op_sel_hi:[1,0,1]
	v_pk_fma_f32 v[146:147], v[26:27], v[192:193], v[138:139] op_sel_hi:[1,0,1]
	v_pk_fma_f32 v[144:145], v[24:25], v[192:193], v[136:137] op_sel_hi:[1,0,1]
	global_store_dwordx4 v[148:149], v[144:147], off offset:16
	v_cndmask_b32_e32 v224, v173, v175, vcc
	v_pk_fma_f32 v[140:141], v[12:13], v[194:195], v[140:141] op_sel_hi:[1,0,1]
	v_pk_fma_f32 v[146:147], v[22:23], v[192:193], v[134:135] op_sel_hi:[1,0,1]
	v_pk_fma_f32 v[144:145], v[20:21], v[192:193], v[132:133] op_sel_hi:[1,0,1]
	global_store_dwordx4 v[148:149], v[144:147], off offset:512
	v_pk_fma_f32 v[138:139], v[10:11], v[194:195], v[138:139] op_sel_hi:[1,0,1]
	v_pk_fma_f32 v[136:137], v[8:9], v[194:195], v[136:137] op_sel_hi:[1,0,1]
	v_pk_fma_f32 v[146:147], v[18:19], v[192:193], v[130:131] op_sel_hi:[1,0,1]
	v_pk_fma_f32 v[144:145], v[16:17], v[192:193], v[128:129] op_sel_hi:[1,0,1]
	global_store_dwordx4 v[148:149], v[144:147], off offset:528
	v_pk_fma_f32 v[134:135], v[6:7], v[194:195], v[134:135] op_sel_hi:[1,0,1]
	v_pk_fma_f32 v[132:133], v[4:5], v[194:195], v[132:133] op_sel_hi:[1,0,1]
	v_add_u32_e32 v146, 0xb0, v160
	v_add_u32_e32 v144, 0xffffc0b0, v160
	v_ashrrev_i32_e32 v145, 31, v146
	v_cndmask_b32_e32 v145, 0, v145, vcc
	v_cndmask_b32_e32 v144, v144, v146, vcc
	v_lshl_add_u64 v[146:147], s[42:43], 0, v[224:225]
	v_lshlrev_b64 v[144:145], 10, v[144:145]
	v_lshl_add_u64 v[144:145], v[146:147], 0, v[144:145]
	v_lshl_add_u64 v[144:145], v[144:145], 0, v[196:197]
	v_pk_fma_f32 v[130:131], v[2:3], v[194:195], v[130:131] op_sel_hi:[1,0,1]
	v_pk_fma_f32 v[128:129], v[0:1], v[194:195], v[128:129] op_sel_hi:[1,0,1]
	global_store_dwordx4 v[144:145], v[140:143], off
	global_store_dwordx4 v[144:145], v[136:139], off offset:16
	global_store_dwordx4 v[144:145], v[132:135], off offset:512
	global_store_dwordx4 v[144:145], v[128:131], off offset:528

; DI float sum16(const float* p) { const f32x4* q = (const f32x4*)p; f32x4 a = q[0], b = q[1], c = q[2], d = q[3]; f32x4 s = (a + b) + (c + d); return (s[0] + s[1]) + (s[2] + s[3]); }
;     template <int PN> DI void body(AccRef acc, const Unit& u, int wr, int wc, int fr, int fq) const {
;     ...
;         for (int ai = 0; ai < 2; ++ai) {
;             const int rb_ = u.pm * 256 + ai * 128 + wr * 64 + fr;
; #pragma unroll
;             for (int m = 0; m < 4; ++m) rinvh[ai][m] = rsqrtf(sum16(ssq + (size_t)(rb_ + 16 * m + zdep) * 16) * (1.f / 1024.f) + EPS);
;             asm volatile("v_mov_b32 %0, 0" : "=v"(zdep) : "v"(rinvh[ai][0]), "v"(rinvh[ai][1]), "v"(rinvh[ai][2]), "v"(rinvh[ai][3]));
;         }
;     DI void operator()(AccRef acc, const Unit& u, int wr, int wc, int fr, int fq) const {
;         switch (u.pn) {
;             case 0: body<0>(acc, u, wr, wc, fr, fq); break;
;             case 1: body<1>(acc, u, wr, wc, fr, fq); break;
;             case 2: body<2>(acc, u, wr, wc, fr, fq); break;
;             case 3: body<3>(acc, u, wr, wc, fr, fq); break;
;             case 4: body<4>(acc, u, wr, wc, fr, fq); break;
;             case 5: body<5>(acc, u, wr, wc, fr, fq); break;
;             case 6: body<6>(acc, u, wr, wc, fr, fq); break;
;             case 7: body<7>(acc, u, wr, wc, fr, fq); break;
;             case 8: body<8>(acc, u, wr, wc, fr, fq); break;
;             default: body<9>(acc, u, wr, wc, fr, fq); break;
.LBB0_1709:
	v_readlane_b32 s4, v253, 32
	v_mbcnt_lo_u32_b32 v128, -1, 0
	v_mbcnt_hi_u32_b32 v128, -1, v128
	s_mov_b32 s54, s39
	v_and_b32_e32 v214, 15, v128
	v_bfe_u32 v213, v128, 4, 2
	s_lshl_b32 s98, s29, 6
	s_lshl_b32 s99, s34, 8
	s_add_i32 s98, s98, s99
	v_add_u32_e32 v248, s98, v214
	v_lshlrev_b32_e32 v248, 6, v248
	v_lshl_add_u32 v248, v213, 4, v248
	global_load_dwordx4 v[244:247], v248, s[70:71]
	global_load_dwordx4 v[244:247], v248, s[70:71] offset:1024
	global_load_dwordx4 v[244:247], v248, s[70:71] offset:2048
	global_load_dwordx4 v[244:247], v248, s[70:71] offset:3072
	v_add_u32_e32 v248, 0x2000, v248
	global_load_dwordx4 v[244:247], v248, s[70:71]
	global_load_dwordx4 v[244:247], v248, s[70:71] offset:1024
	global_load_dwordx4 v[244:247], v248, s[70:71] offset:2048
	global_load_dwordx4 v[244:247], v248, s[70:71] offset:3072
	s_mov_b32 s43, s29
	s_mov_b64 s[4:5], -1
	s_mov_b64 s[10:11], 0
	s_cmp_lt_i32 s66, 4
	s_mov_b64 s[80:81], 0
	s_cbranch_scc1 .LBB0_1744
	s_cmp_gt_i32 s66, 5
	s_cbranch_scc0 .LBB0_1738
	s_cmp_gt_i32 s66, 6
	s_cbranch_scc0 .LBB0_1735
	s_cmp_gt_i32 s66, 7
	s_cbranch_scc0 .LBB0_1732
	s_cmp_eq_u32 s66, 8
	s_mov_b64 s[80:81], -1
	s_cbranch_scc0 .LBB0_1731
	s_lshl_b32 s4, s43, 6
	s_lshl_b32 s5, s34, 8
	s_add_i32 s4, s4, s5
	v_add_u32_e32 v160, s4, v214
	v_ashrrev_i32_e32 v161, 31, v160
	v_lshlrev_b64 v[128:129], 6, v[160:161]
	v_lshl_add_u64 v[140:141], s[70:71], 0, v[128:129]
	global_load_dwordx4 v[128:131], v[140:141], off offset:32
	global_load_dwordx4 v[132:135], v[140:141], off offset:48
	global_load_dwordx4 v[136:139], v[140:141], off
	s_nop 0
	global_load_dwordx4 v[140:143], v[140:141], off offset:16
	v_add_u32_e32 v190, 16, v160
	v_ashrrev_i32_e32 v191, 31, v190
	s_mov_b32 s4, 0x358637bd
	s_mov_b32 s6, 0x3a800000
	v_add_u32_e32 v166, 32, v160
	v_ashrrev_i32_e32 v167, 31, v166
	v_add_u32_e32 v168, 48, v160
	v_ashrrev_i32_e32 v169, 31, v168
	v_add_u32_e32 v164, 0x80, v160
	s_movk_i32 s8, 0x2800
	s_mov_b64 s[12:13], 0x126000
	s_mov_b32 s9, 0x126000
	v_add_u32_e32 v163, 0xffffc080, v160
	v_mov_b32_e32 v165, 0xffffc400
	v_mov_b32_e32 v171, 0x4000
	s_waitcnt vmcnt(0)
	v_pk_add_f32 v[130:131], v[130:131], v[134:135]
	v_pk_add_f32 v[128:129], v[128:129], v[132:133]
	v_pk_add_f32 v[138:139], v[138:139], v[142:143]
	v_pk_add_f32 v[136:137], v[136:137], v[140:141]
	v_pk_add_f32 v[130:131], v[138:139], v[130:131]
	v_pk_add_f32 v[128:129], v[136:137], v[128:129]
	s_nop 0
	v_pk_mov_b32 v[132:133], v[128:129], v[130:131] op_sel:[1,0]
	v_mov_b32_e32 v129, v131
	v_pk_add_f32 v[144:145], v[132:133], v[128:129]
	v_lshlrev_b64 v[128:129], 6, v[190:191]
	v_lshl_add_u64 v[140:141], s[70:71], 0, v[128:129]
	global_load_dwordx4 v[128:131], v[140:141], off offset:32
	global_load_dwordx4 v[132:135], v[140:141], off offset:48
	global_load_dwordx4 v[136:139], v[140:141], off
	s_nop 0
	global_load_dwordx4 v[140:143], v[140:141], off offset:16
	s_waitcnt vmcnt(2)
	v_pk_add_f32 v[130:131], v[130:131], v[134:135]
	v_pk_add_f32 v[128:129], v[128:129], v[132:133]
	s_waitcnt vmcnt(0)
	v_pk_add_f32 v[138:139], v[138:139], v[142:143]
	v_pk_add_f32 v[136:137], v[136:137], v[140:141]
	v_pk_add_f32 v[130:131], v[138:139], v[130:131]
	v_pk_add_f32 v[128:129], v[136:137], v[128:129]
	s_nop 0
	v_pk_mov_b32 v[132:133], v[128:129], v[130:131] op_sel:[1,0]
	v_mov_b32_e32 v129, v131
	v_pk_add_f32 v[128:129], v[132:133], v[128:129]
	v_mov_b32_e32 v131, v144
	v_mov_b32_e32 v130, v128
	v_mov_b32_e32 v144, v129
	v_pk_add_f32 v[130:131], v[130:131], v[144:145]
	v_mov_b64_e32 v[128:129], s[4:5]
	v_pk_fma_f32 v[130:131], v[130:131], s[6:7], v[128:129] op_sel_hi:[1,0,0]
	s_nop 0
	v_mul_f32_e32 v132, 0x4b800000, v131
	v_cmp_gt_f32_e64 s[4:5], s33, v131
	v_cmp_gt_f32_e32 vcc, s33, v130
	s_nop 0
	v_cndmask_b32_e64 v131, v131, v132, s[4:5]
	v_rsq_f32_e32 v131, v131
	s_nop 0
	v_mul_f32_e32 v132, 0x45800000, v131
	v_cndmask_b32_e64 v192, v131, v132, s[4:5]
	v_mul_f32_e32 v131, 0x4b800000, v130
	v_cndmask_b32_e32 v130, v130, v131, vcc
	v_rsq_f32_e32 v130, v130
	s_nop 0
	v_mul_f32_e32 v131, 0x45800000, v130
	v_cndmask_b32_e32 v162, v130, v131, vcc
	v_lshlrev_b64 v[130:131], 6, v[166:167]
	v_lshl_add_u64 v[142:143], s[70:71], 0, v[130:131]
	global_load_dwordx4 v[130:133], v[142:143], off offset:32
	global_load_dwordx4 v[134:137], v[142:143], off offset:48
	global_load_dwordx4 v[138:141], v[142:143], off
	s_nop 0
	global_load_dwordx4 v[142:145], v[142:143], off offset:16
	s_waitcnt vmcnt(2)
	v_pk_add_f32 v[132:133], v[132:133], v[136:137]
	v_pk_add_f32 v[130:131], v[130:131], v[134:135]
	s_waitcnt vmcnt(0)
	v_pk_add_f32 v[140:141], v[140:141], v[144:145]
	v_pk_add_f32 v[138:139], v[138:139], v[142:143]
	v_pk_add_f32 v[132:133], v[140:141], v[132:133]
	v_pk_add_f32 v[130:131], v[138:139], v[130:131]
	s_nop 0
	v_pk_mov_b32 v[134:135], v[130:131], v[132:133] op_sel:[1,0]
	v_mov_b32_e32 v131, v133
	v_pk_add_f32 v[146:147], v[134:135], v[130:131]
	v_lshlrev_b64 v[130:131], 6, v[168:169]
	v_lshl_add_u64 v[142:143], s[70:71], 0, v[130:131]
	global_load_dwordx4 v[130:133], v[142:143], off offset:32
	global_load_dwordx4 v[134:137], v[142:143], off offset:48
	global_load_dwordx4 v[138:141], v[142:143], off
	s_nop 0
	global_load_dwordx4 v[142:145], v[142:143], off offset:16
	s_waitcnt vmcnt(2)
	v_pk_add_f32 v[132:133], v[132:133], v[136:137]
	v_pk_add_f32 v[130:131], v[130:131], v[134:135]
	s_waitcnt vmcnt(0)
; DI float sum16(const float* p) { const f32x4* q = (const f32x4*)p; f32x4 a = q[0], b = q[1], c = q[2], d = q[3]; f32x4 s = (a + b) + (c + d); return (s[0] + s[1]) + (s[2] + s[3]); }
;     template <int PN> DI void body(AccRef acc, const Unit& u, int wr, int wc, int fr, int fq) const {
;     ...
;         for (int ai = 0; ai < 2; ++ai) {
;             const int rb_ = u.pm * 256 + ai * 128 + wr * 64 + fr;
; #pragma unroll
;             for (int m = 0; m < 4; ++m) rinvh[ai][m] = rsqrtf(sum16(ssq + (size_t)(rb_ + 16 * m + zdep) * 16) * (1.f / 1024.f) + EPS);
;             asm volatile("v_mov_b32 %0, 0" : "=v"(zdep) : "v"(rinvh[ai][0]), "v"(rinvh[ai][1]), "v"(rinvh[ai][2]), "v"(rinvh[ai][3]));
;         }
	v_pk_add_f32 v[140:141], v[140:141], v[144:145]
	v_pk_add_f32 v[138:139], v[138:139], v[142:143]
	v_pk_add_f32 v[132:133], v[140:141], v[132:133]
	v_pk_add_f32 v[130:131], v[138:139], v[130:131]
	s_nop 0
	v_pk_mov_b32 v[134:135], v[130:131], v[132:133] op_sel:[1,0]
	v_mov_b32_e32 v131, v133
	v_pk_add_f32 v[130:131], v[134:135], v[130:131]
	v_mov_b32_e32 v133, v146
	v_mov_b32_e32 v132, v130
	v_mov_b32_e32 v146, v131
	v_pk_add_f32 v[130:131], v[132:133], v[146:147]
	s_nop 0
	v_pk_fma_f32 v[130:131], v[130:131], s[6:7], v[128:129] op_sel_hi:[1,0,0]
	s_nop 0
	v_mul_f32_e32 v132, 0x4b800000, v131
	v_cmp_gt_f32_e64 s[4:5], s33, v131
	v_cmp_gt_f32_e32 vcc, s33, v130
	s_nop 0
	v_cndmask_b32_e64 v131, v131, v132, s[4:5]
	v_rsq_f32_e32 v131, v131
	s_nop 0
	v_mul_f32_e32 v132, 0x45800000, v131
	v_cndmask_b32_e64 v172, v131, v132, s[4:5]
	v_mul_f32_e32 v131, 0x4b800000, v130
	v_cndmask_b32_e32 v130, v130, v131, vcc
	v_rsq_f32_e32 v130, v130
	s_nop 0
	v_mul_f32_e32 v131, 0x45800000, v130
	v_cndmask_b32_e32 v188, v130, v131, vcc
	v_mov_b32 v130, 0
	s_nop 0
	v_add_u32_e32 v130, v130, v164
	v_ashrrev_i32_e32 v131, 31, v130
	v_lshlrev_b64 v[132:133], 6, v[130:131]
	v_lshl_add_u64 v[144:145], s[70:71], 0, v[132:133]
	global_load_dwordx4 v[132:135], v[144:145], off offset:32
	global_load_dwordx4 v[136:139], v[144:145], off offset:48
	global_load_dwordx4 v[140:143], v[144:145], off
	s_nop 0
	global_load_dwordx4 v[144:147], v[144:145], off offset:16
	s_waitcnt vmcnt(2)
	v_pk_add_f32 v[134:135], v[134:135], v[138:139]
	v_pk_add_f32 v[132:133], v[132:133], v[136:137]
	s_waitcnt vmcnt(0)
	v_pk_add_f32 v[142:143], v[142:143], v[146:147]
	v_pk_add_f32 v[140:141], v[140:141], v[144:145]
	v_pk_add_f32 v[134:135], v[142:143], v[134:135]
	v_pk_add_f32 v[132:133], v[140:141], v[132:133]
	s_nop 0
	v_pk_mov_b32 v[136:137], v[132:133], v[134:135] op_sel:[1,0]
	v_mov_b32_e32 v133, v135
	v_pk_add_f32 v[148:149], v[136:137], v[132:133]
	v_add_u32_e32 v132, 16, v130
	v_ashrrev_i32_e32 v133, 31, v132
	v_lshlrev_b64 v[132:133], 6, v[132:133]
	v_lshl_add_u64 v[144:145], s[70:71], 0, v[132:133]
	global_load_dwordx4 v[132:135], v[144:145], off offset:32
	global_load_dwordx4 v[136:139], v[144:145], off offset:48
	global_load_dwordx4 v[140:143], v[144:145], off
	s_nop 0
	global_load_dwordx4 v[144:147], v[144:145], off offset:16
	s_waitcnt vmcnt(2)
	v_pk_add_f32 v[134:135], v[134:135], v[138:139]
	v_pk_add_f32 v[132:133], v[132:133], v[136:137]
	s_waitcnt vmcnt(0)
	v_pk_add_f32 v[142:143], v[142:143], v[146:147]
	v_pk_add_f32 v[140:141], v[140:141], v[144:145]
	v_pk_add_f32 v[134:135], v[142:143], v[134:135]
	v_pk_add_f32 v[132:133], v[140:141], v[132:133]
	s_nop 0
	v_pk_mov_b32 v[136:137], v[132:133], v[134:135] op_sel:[1,0]
	v_mov_b32_e32 v133, v135
	v_pk_add_f32 v[132:133], v[136:137], v[132:133]
	v_mov_b32_e32 v135, v148
	v_mov_b32_e32 v134, v132
	v_mov_b32_e32 v148, v133
	v_pk_add_f32 v[132:133], v[134:135], v[148:149]
	s_nop 0
	v_pk_fma_f32 v[132:133], v[132:133], s[6:7], v[128:129] op_sel_hi:[1,0,0]
	s_nop 0
	v_mul_f32_e32 v131, 0x4b800000, v133
	v_cmp_gt_f32_e64 s[4:5], s33, v133
	v_cmp_gt_f32_e32 vcc, s33, v132
	s_nop 0
	v_cndmask_b32_e64 v131, v133, v131, s[4:5]
	v_rsq_f32_e32 v131, v131
	s_nop 0
	v_mul_f32_e32 v133, 0x45800000, v131
	v_cndmask_b32_e64 v174, v131, v133, s[4:5]
	v_mul_f32_e32 v131, 0x4b800000, v132
	v_cndmask_b32_e32 v131, v132, v131, vcc
	v_rsq_f32_e32 v131, v131
	s_nop 0
	v_mul_f32_e32 v132, 0x45800000, v131
	v_cndmask_b32_e32 v170, v131, v132, vcc
	v_add_u32_e32 v132, 32, v130
	v_ashrrev_i32_e32 v133, 31, v132
	v_lshlrev_b64 v[132:133], 6, v[132:133]
	v_lshl_add_u64 v[144:145], s[70:71], 0, v[132:133]
	global_load_dwordx4 v[132:135], v[144:145], off offset:32
	global_load_dwordx4 v[136:139], v[144:145], off offset:48
	global_load_dwordx4 v[140:143], v[144:145], off
	s_nop 0
	global_load_dwordx4 v[144:147], v[144:145], off offset:16
	v_add_u32_e32 v130, 48, v130
	v_ashrrev_i32_e32 v131, 31, v130
	v_lshlrev_b64 v[130:131], 6, v[130:131]
	s_waitcnt vmcnt(2)
	v_pk_add_f32 v[134:135], v[134:135], v[138:139]
	v_pk_add_f32 v[132:133], v[132:133], v[136:137]
	s_waitcnt vmcnt(0)
	v_pk_add_f32 v[142:143], v[142:143], v[146:147]
	v_pk_add_f32 v[140:141], v[140:141], v[144:145]
	v_pk_add_f32 v[134:135], v[142:143], v[134:135]
	v_pk_add_f32 v[132:133], v[140:141], v[132:133]
	v_lshl_add_u64 v[142:143], s[70:71], 0, v[130:131]
	v_pk_mov_b32 v[136:137], v[132:133], v[134:135] op_sel:[1,0]
	v_mov_b32_e32 v133, v135
	v_pk_add_f32 v[146:147], v[136:137], v[132:133]
	global_load_dwordx4 v[130:133], v[142:143], off offset:32
	global_load_dwordx4 v[134:137], v[142:143], off offset:48
	global_load_dwordx4 v[138:141], v[142:143], off
	s_nop 0
	global_load_dwordx4 v[142:145], v[142:143], off offset:16
	s_waitcnt vmcnt(2)
	v_pk_add_f32 v[132:133], v[132:133], v[136:137]
	v_pk_add_f32 v[130:131], v[130:131], v[134:135]
	s_waitcnt vmcnt(0)
;     template <int PN> DI void body(AccRef acc, const Unit& u, int wr, int wc, int fr, int fq) const {
;     ...
; #pragma unroll
;         for (int ai = 0; ai < 2; ++ai) {
;             const int rb_ = u.pm * 256 + ai * 128 + wr * 64 + fr;
;             int mb_, p_, k_; row_info(rb_, mb_, p_, k_);
; #pragma unroll
;             for (int bj = 0; bj < 2; ++bj)
; #pragma unroll
;                 for (int n = 0; n < 2; ++n) cvh[ai][bj][n] = *(const f32x4*)(cv + (size_t)(mb_ + zdep) * NIN + PN * 256 + bj * 128 + cl + 4 * n);
;         }
;     ...
;                     float* lo = orow(out, l, row, PN == 8 ? O_PSK : O_PSV, PN == 8 ? O_SSK : O_SSV, 256);
; #pragma unroll
;                     for (int bj = 0; bj < 2; ++bj) {
;                         *(f32x4*)(lo + bj * 128 + cl) = (f32x4){v[bj][0], v[bj][1], v[bj][2], v[bj][3]};
;                         *(f32x4*)(lo + bj * 128 + cl + 4) = (f32x4){v[bj][4], v[bj][5], v[bj][6], v[bj][7]};
;                     }
	v_pk_add_f32 v[140:141], v[140:141], v[144:145]
	v_pk_add_f32 v[138:139], v[138:139], v[142:143]
	v_pk_add_f32 v[132:133], v[140:141], v[132:133]
	v_pk_add_f32 v[130:131], v[138:139], v[130:131]
	s_nop 0
	v_pk_mov_b32 v[134:135], v[130:131], v[132:133] op_sel:[1,0]
	v_mov_b32_e32 v131, v133
	v_pk_add_f32 v[130:131], v[134:135], v[130:131]
	v_mov_b32_e32 v133, v146
	v_mov_b32_e32 v132, v130
	v_mov_b32_e32 v146, v131
	v_pk_add_f32 v[130:131], v[132:133], v[146:147]
	s_nop 0
	v_pk_fma_f32 v[128:129], v[130:131], s[6:7], v[128:129] op_sel_hi:[1,0,0]
	s_nop 0
	v_mul_f32_e32 v130, 0x4b800000, v129
	v_cmp_gt_f32_e64 s[4:5], s33, v129
	v_cmp_gt_f32_e32 vcc, s33, v128
	s_nop 0
	v_cndmask_b32_e64 v129, v129, v130, s[4:5]
	v_rsq_f32_e32 v129, v129
	s_nop 0
	v_mul_f32_e32 v130, 0x45800000, v129
	v_cndmask_b32_e64 v196, v129, v130, s[4:5]
	v_mul_f32_e32 v129, 0x4b800000, v128
	v_cndmask_b32_e32 v128, v128, v129, vcc
	v_rsq_f32_e32 v128, v128
	s_lshl_b32 s4, s54, 5
	v_lshl_add_u32 v198, v213, 3, s4
	v_cmp_gt_i32_e64 s[4:5], s94, v160
	v_mul_f32_e32 v129, 0x45800000, v128
	v_cndmask_b32_e32 v194, v128, v129, vcc
	v_add_u32_e32 v129, 0xffffc000, v160
	v_lshrrev_b32_e32 v129, 6, v129
	v_ashrrev_i32_e32 v128, 11, v160
	v_add_u32_e32 v129, 8, v129
	v_cndmask_b32_e64 v128, v129, v128, s[4:5]
	v_mov_b32 v134, 0
	v_ashrrev_i32_e32 v199, 31, v198
	v_add_u32_e32 v130, v134, v128
	v_mov_b64_e32 v[128:129], s[60:61]
	v_mad_i64_i32 v[130:131], s[6:7], v130, s8, v[128:129]
	v_lshlrev_b64 v[200:201], 2, v[198:199]
	v_lshl_add_u64 v[130:131], v[130:131], 0, v[200:201]
	v_lshl_add_u64 v[132:133], v[130:131], 0, s[12:13]
	v_add_co_u32_e32 v130, vcc, s9, v130
	s_movk_i32 s6, 0x3fff
	s_nop 0
	v_addc_co_u32_e32 v131, vcc, 0, v131, vcc
	global_load_dwordx4 v[152:155], v[130:131], off
	global_load_dwordx4 v[156:159], v[132:133], off offset:16
	global_load_dwordx4 v[144:147], v[132:133], off offset:528
	global_load_dwordx4 v[148:151], v[132:133], off offset:512
	v_lshrrev_b32_e32 v131, 6, v163
	v_cmp_lt_i32_e32 vcc, s6, v164
	v_cmp_gt_i32_e64 s[6:7], s94, v164
	v_ashrrev_i32_e32 v130, 11, v164
	v_add_u32_e32 v131, 8, v131
	v_cndmask_b32_e64 v130, v131, v130, s[6:7]
	v_add_u32_e32 v130, v134, v130
	v_mad_i64_i32 v[128:129], s[6:7], v130, s8, v[128:129]
	v_lshl_add_u64 v[128:129], v[128:129], 0, v[200:201]
	v_lshl_add_u64 v[132:133], v[128:129], 0, s[12:13]
	v_add_co_u32_e64 v128, s[6:7], s9, v128
	v_cndmask_b32_e64 v203, -1, 0, s[4:5]
	s_nop 0
	v_addc_co_u32_e64 v129, s[6:7], 0, v129, s[6:7]
	global_load_dwordx4 v[140:143], v[128:129], off
	global_load_dwordx4 v[136:139], v[132:133], off offset:16
	s_nop 0
	global_load_dwordx4 v[128:131], v[132:133], off offset:528
	s_nop 0
	global_load_dwordx4 v[132:135], v[132:133], off offset:512
	v_cndmask_b32_e64 v202, v165, v171, s[4:5]
	v_mov_b32_e32 v165, 0xab98000
	v_mov_b32_e32 v171, 0x6800000
	v_lshl_add_u64 v[202:203], v[202:203], 0, v[160:161]
	v_cndmask_b32_e64 v224, v165, v171, s[4:5]
	v_lshl_add_u64 v[204:205], s[84:85], 0, v[224:225]
	v_lshlrev_b64 v[202:203], 10, v[202:203]
	v_lshl_add_u64 v[202:203], v[204:205], 0, v[202:203]
	v_lshl_add_u64 v[206:207], v[202:203], 0, v[200:201]
	s_movk_i32 s6, 0xc410
	v_mov_b32_e32 v224, v160
	s_mov_b32 s7, -1
	v_cmp_gt_i32_e64 s[4:5], s82, v160
	s_movk_i32 s8, 0xc420
	s_mov_b32 s9, -1
	s_waitcnt vmcnt(7)
	v_pk_fma_f32 v[204:205], v[126:127], v[192:193], v[154:155] op_sel_hi:[1,0,1]
	v_pk_fma_f32 v[202:203], v[124:125], v[192:193], v[152:153] op_sel_hi:[1,0,1]
	global_store_dwordx4 v[206:207], v[202:205], off
	s_waitcnt vmcnt(7)
	s_nop 0
	v_pk_fma_f32 v[204:205], v[122:123], v[192:193], v[158:159] op_sel_hi:[1,0,1]
	v_pk_fma_f32 v[202:203], v[120:121], v[192:193], v[156:157] op_sel_hi:[1,0,1]
	global_store_dwordx4 v[206:207], v[202:205], off offset:16
	s_waitcnt vmcnt(6)
	s_nop 0
	v_pk_fma_f32 v[204:205], v[118:119], v[192:193], v[150:151] op_sel_hi:[1,0,1]
	v_pk_fma_f32 v[202:203], v[116:117], v[192:193], v[148:149] op_sel_hi:[1,0,1]
	global_store_dwordx4 v[206:207], v[202:205], off offset:512
	s_nop 1
	v_pk_fma_f32 v[204:205], v[114:115], v[192:193], v[146:147] op_sel_hi:[1,0,1]
	v_pk_fma_f32 v[202:203], v[112:113], v[192:193], v[144:145] op_sel_hi:[1,0,1]
	v_lshl_add_u64 v[192:193], v[224:225], 0, s[6:7]
	s_mov_b64 s[6:7], 0x4000
	v_lshl_add_u64 v[190:191], v[190:191], 0, s[6:7]
	v_cndmask_b32_e64 v191, v193, v191, s[4:5]
	v_cndmask_b32_e64 v190, v192, v190, s[4:5]
	v_cndmask_b32_e64 v192, v165, v171, s[4:5]
	v_mov_b32_e32 v193, v225
	v_lshl_add_u64 v[192:193], s[84:85], 0, v[192:193]
	v_lshlrev_b64 v[190:191], 10, v[190:191]
	v_lshl_add_u64 v[190:191], v[192:193], 0, v[190:191]
	global_store_dwordx4 v[206:207], v[202:205], off offset:528
	v_pk_fma_f32 v[192:193], v[110:111], v[162:163], v[154:155] op_sel_hi:[1,0,1]
	v_cmp_gt_i32_e64 s[4:5], s83, v160
	v_lshl_add_u64 v[202:203], v[190:191], 0, v[200:201]
	v_pk_fma_f32 v[190:191], v[108:109], v[162:163], v[152:153] op_sel_hi:[1,0,1]
	global_store_dwordx4 v[202:203], v[190:193], off
	v_lshl_add_u64 v[166:167], v[166:167], 0, s[6:7]
	s_nop 0
	v_pk_fma_f32 v[192:193], v[106:107], v[162:163], v[158:159] op_sel_hi:[1,0,1]
	v_pk_fma_f32 v[190:191], v[104:105], v[162:163], v[156:157] op_sel_hi:[1,0,1]
	global_store_dwordx4 v[202:203], v[190:193], off offset:16
	s_nop 1
	v_pk_fma_f32 v[192:193], v[102:103], v[162:163], v[150:151] op_sel_hi:[1,0,1]
	v_pk_fma_f32 v[190:191], v[100:101], v[162:163], v[148:149] op_sel_hi:[1,0,1]
	global_store_dwordx4 v[202:203], v[190:193], off offset:512
	s_nop 1
	v_pk_fma_f32 v[192:193], v[98:99], v[162:163], v[146:147] op_sel_hi:[1,0,1]
	v_pk_fma_f32 v[190:191], v[96:97], v[162:163], v[144:145] op_sel_hi:[1,0,1]
;     template <int PN> DI void body(AccRef acc, const Unit& u, int wr, int wc, int fr, int fq) const {
;     ...
;                     float* lo = orow(out, l, row, PN == 8 ? O_PSK : O_PSV, PN == 8 ? O_SSK : O_SSV, 256);
; #pragma unroll
;                     for (int bj = 0; bj < 2; ++bj) {
;                         *(f32x4*)(lo + bj * 128 + cl) = (f32x4){v[bj][0], v[bj][1], v[bj][2], v[bj][3]};
;                         *(f32x4*)(lo + bj * 128 + cl + 4) = (f32x4){v[bj][4], v[bj][5], v[bj][6], v[bj][7]};
;                     }
	global_store_dwordx4 v[202:203], v[190:193], off offset:528
	s_nop 1
	v_lshl_add_u64 v[190:191], v[224:225], 0, s[8:9]
	v_cndmask_b32_e64 v167, v191, v167, s[4:5]
	v_cndmask_b32_e64 v166, v190, v166, s[4:5]
	v_cndmask_b32_e64 v190, v165, v171, s[4:5]
	v_mov_b32_e32 v191, v225
	v_lshl_add_u64 v[190:191], s[84:85], 0, v[190:191]
	v_lshlrev_b64 v[166:167], 10, v[166:167]
	v_lshl_add_u64 v[166:167], v[190:191], 0, v[166:167]
	v_lshl_add_u64 v[166:167], v[166:167], 0, v[200:201]
	v_pk_fma_f32 v[192:193], v[94:95], v[172:173], v[154:155] op_sel_hi:[1,0,1]
	v_pk_fma_f32 v[190:191], v[92:93], v[172:173], v[152:153] op_sel_hi:[1,0,1]
	global_store_dwordx4 v[166:167], v[190:193], off
	s_movk_i32 s8, 0xc430
	s_mov_b32 s9, -1
	v_pk_fma_f32 v[192:193], v[90:91], v[172:173], v[158:159] op_sel_hi:[1,0,1]
	v_pk_fma_f32 v[190:191], v[88:89], v[172:173], v[156:157] op_sel_hi:[1,0,1]
	global_store_dwordx4 v[166:167], v[190:193], off offset:16
	v_cmp_gt_i32_e64 s[4:5], s92, v160
	v_lshl_add_u64 v[160:161], v[224:225], 0, s[8:9]
	v_pk_fma_f32 v[192:193], v[86:87], v[172:173], v[150:151] op_sel_hi:[1,0,1]
	v_pk_fma_f32 v[190:191], v[84:85], v[172:173], v[148:149] op_sel_hi:[1,0,1]
	global_store_dwordx4 v[166:167], v[190:193], off offset:512
	v_pk_fma_f32 v[154:155], v[78:79], v[188:189], v[154:155] op_sel_hi:[1,0,1]
	v_pk_fma_f32 v[152:153], v[76:77], v[188:189], v[152:153] op_sel_hi:[1,0,1]
	v_pk_fma_f32 v[192:193], v[82:83], v[172:173], v[146:147] op_sel_hi:[1,0,1]
	v_pk_fma_f32 v[190:191], v[80:81], v[172:173], v[144:145] op_sel_hi:[1,0,1]
	global_store_dwordx4 v[166:167], v[190:193], off offset:528
	v_lshl_add_u64 v[166:167], v[168:169], 0, s[6:7]
	v_cndmask_b32_e64 v161, v161, v167, s[4:5]
	v_cndmask_b32_e64 v160, v160, v166, s[4:5]
	v_cndmask_b32_e64 v166, v165, v171, s[4:5]
	v_mov_b32_e32 v167, v225
	v_lshl_add_u64 v[166:167], s[84:85], 0, v[166:167]
	v_lshlrev_b64 v[160:161], 10, v[160:161]
	v_lshl_add_u64 v[160:161], v[166:167], 0, v[160:161]
	v_lshl_add_u64 v[160:161], v[160:161], 0, v[200:201]
	global_store_dwordx4 v[160:161], v[152:155], off
	v_pk_fma_f32 v[150:151], v[70:71], v[188:189], v[150:151] op_sel_hi:[1,0,1]
	v_pk_fma_f32 v[148:149], v[68:69], v[188:189], v[148:149] op_sel_hi:[1,0,1]
	v_pk_fma_f32 v[154:155], v[74:75], v[188:189], v[158:159] op_sel_hi:[1,0,1]
	v_pk_fma_f32 v[152:153], v[72:73], v[188:189], v[156:157] op_sel_hi:[1,0,1]
	v_pk_fma_f32 v[146:147], v[66:67], v[188:189], v[146:147] op_sel_hi:[1,0,1]
	v_pk_fma_f32 v[144:145], v[64:65], v[188:189], v[144:145] op_sel_hi:[1,0,1]
	global_store_dwordx4 v[160:161], v[152:155], off offset:16
	global_store_dwordx4 v[160:161], v[148:151], off offset:512
	global_store_dwordx4 v[160:161], v[144:147], off offset:528
	s_and_saveexec_b64 s[4:5], vcc
	s_xor_b64 s[4:5], exec, s[4:5]
	v_add_u32_e32 v144, 0x400, v163
	v_mov_b32_e32 v145, v225
	s_or_saveexec_b64 s[4:5], s[4:5]
	v_mov_b64_e32 v[146:147], 0x2ae6000
	s_xor_b64 exec, exec, s[4:5]
	v_ashrrev_i32_e32 v165, 31, v164
	v_lshl_add_u64 v[144:145], v[164:165], 0, s[6:7]
	v_mov_b64_e32 v[146:147], 0x1a00000
	s_or_b64 exec, exec, s[4:5]
	v_lshlrev_b32_e32 v146, 2, v146
	v_mov_b32_e32 v147, v225
	v_lshl_add_u64 v[146:147], s[84:85], 0, v[146:147]
	v_lshlrev_b64 v[144:145], 10, v[144:145]
	v_lshl_add_u64 v[144:145], v[146:147], 0, v[144:145]
	v_lshl_add_u64 v[148:149], v[198:199], 2, v[144:145]
	s_waitcnt vmcnt(19)
	v_pk_fma_f32 v[146:147], v[62:63], v[174:175], v[142:143] op_sel_hi:[1,0,1]
	v_pk_fma_f32 v[144:145], v[60:61], v[174:175], v[140:141] op_sel_hi:[1,0,1]
	global_store_dwordx4 v[148:149], v[144:147], off
	s_movk_i32 s4, 0x3fef
	v_cmp_lt_i32_e32 vcc, s4, v164
	s_waitcnt vmcnt(19)
	v_pk_fma_f32 v[146:147], v[58:59], v[174:175], v[138:139] op_sel_hi:[1,0,1]
	v_pk_fma_f32 v[144:145], v[56:57], v[174:175], v[136:137] op_sel_hi:[1,0,1]
	global_store_dwordx4 v[148:149], v[144:147], off offset:16
	s_waitcnt vmcnt(18)
;     template <int PN> DI void body(AccRef acc, const Unit& u, int wr, int wc, int fr, int fq) const {
;     ...
;                     float* lo = orow(out, l, row, PN == 8 ? O_PSK : O_PSV, PN == 8 ? O_SSK : O_SSV, 256);
; #pragma unroll
;                     for (int bj = 0; bj < 2; ++bj) {
;                         *(f32x4*)(lo + bj * 128 + cl) = (f32x4){v[bj][0], v[bj][1], v[bj][2], v[bj][3]};
;                         *(f32x4*)(lo + bj * 128 + cl + 4) = (f32x4){v[bj][4], v[bj][5], v[bj][6], v[bj][7]};
;                     }
	s_nop 0
	v_pk_fma_f32 v[146:147], v[54:55], v[174:175], v[134:135] op_sel_hi:[1,0,1]
	v_pk_fma_f32 v[144:145], v[52:53], v[174:175], v[132:133] op_sel_hi:[1,0,1]
	global_store_dwordx4 v[148:149], v[144:147], off offset:512
	s_nop 1
	v_pk_fma_f32 v[146:147], v[50:51], v[174:175], v[130:131] op_sel_hi:[1,0,1]
	v_pk_fma_f32 v[144:145], v[48:49], v[174:175], v[128:129] op_sel_hi:[1,0,1]
	global_store_dwordx4 v[148:149], v[144:147], off offset:528
	s_and_saveexec_b64 s[4:5], vcc
	s_xor_b64 s[4:5], exec, s[4:5]
	s_movk_i32 s6, 0xc490
	s_mov_b32 s7, -1
	v_lshl_add_u64 v[144:145], v[224:225], 0, s[6:7]
	s_or_saveexec_b64 s[4:5], s[4:5]
	v_mov_b64_e32 v[146:147], 0x2ae6000
	s_xor_b64 exec, exec, s[4:5]
	v_add_u32_e32 v144, 0x90, v224
	v_ashrrev_i32_e32 v145, 31, v144
	s_mov_b64 s[6:7], 0x4000
	v_lshl_add_u64 v[144:145], v[144:145], 0, s[6:7]
	v_mov_b64_e32 v[146:147], 0x1a00000
	s_or_b64 exec, exec, s[4:5]
	v_lshlrev_b32_e32 v146, 2, v146
	v_mov_b32_e32 v147, v225
	v_lshl_add_u64 v[146:147], s[84:85], 0, v[146:147]
	v_lshlrev_b64 v[144:145], 10, v[144:145]
	v_lshl_add_u64 v[144:145], v[146:147], 0, v[144:145]
	v_lshl_add_u64 v[148:149], v[198:199], 2, v[144:145]
	v_pk_fma_f32 v[146:147], v[46:47], v[170:171], v[142:143] op_sel_hi:[1,0,1]
	v_pk_fma_f32 v[144:145], v[44:45], v[170:171], v[140:141] op_sel_hi:[1,0,1]
	global_store_dwordx4 v[148:149], v[144:147], off
	s_movk_i32 s4, 0x3fdf
	v_cmp_lt_i32_e32 vcc, s4, v164
	v_pk_fma_f32 v[146:147], v[42:43], v[170:171], v[138:139] op_sel_hi:[1,0,1]
	v_pk_fma_f32 v[144:145], v[40:41], v[170:171], v[136:137] op_sel_hi:[1,0,1]
	global_store_dwordx4 v[148:149], v[144:147], off offset:16
	s_nop 1
	v_pk_fma_f32 v[146:147], v[38:39], v[170:171], v[134:135] op_sel_hi:[1,0,1]
	v_pk_fma_f32 v[144:145], v[36:37], v[170:171], v[132:133] op_sel_hi:[1,0,1]
	global_store_dwordx4 v[148:149], v[144:147], off offset:512
	s_nop 1
	v_pk_fma_f32 v[146:147], v[30:31], v[170:171], v[130:131] op_sel_hi:[1,0,1]
	v_pk_fma_f32 v[144:145], v[28:29], v[170:171], v[128:129] op_sel_hi:[1,0,1]
	global_store_dwordx4 v[148:149], v[144:147], off offset:528
	s_and_saveexec_b64 s[4:5], vcc
	s_xor_b64 s[4:5], exec, s[4:5]
	s_movk_i32 s6, 0xc4a0
	s_mov_b32 s7, -1
	v_lshl_add_u64 v[144:145], v[224:225], 0, s[6:7]
	s_or_saveexec_b64 s[4:5], s[4:5]
	v_mov_b64_e32 v[146:147], 0x2ae6000
	s_xor_b64 exec, exec, s[4:5]
	v_add_u32_e32 v144, 0xa0, v224
	v_ashrrev_i32_e32 v145, 31, v144
	s_mov_b64 s[6:7], 0x4000
	v_lshl_add_u64 v[144:145], v[144:145], 0, s[6:7]
	v_mov_b64_e32 v[146:147], 0x1a00000
	s_or_b64 exec, exec, s[4:5]
	v_lshlrev_b32_e32 v146, 2, v146
	v_mov_b32_e32 v147, v225
	v_lshl_add_u64 v[146:147], s[84:85], 0, v[146:147]
	v_lshlrev_b64 v[144:145], 10, v[144:145]
	v_lshl_add_u64 v[144:145], v[146:147], 0, v[144:145]
	v_lshl_add_u64 v[148:149], v[198:199], 2, v[144:145]
	v_pk_fma_f32 v[146:147], v[34:35], v[196:197], v[142:143] op_sel_hi:[1,0,1]
	v_pk_fma_f32 v[144:145], v[32:33], v[196:197], v[140:141] op_sel_hi:[1,0,1]
	global_store_dwordx4 v[148:149], v[144:147], off
	s_movk_i32 s4, 0x3fcf
	v_cmp_lt_i32_e32 vcc, s4, v164
	v_pk_fma_f32 v[146:147], v[26:27], v[196:197], v[138:139] op_sel_hi:[1,0,1]
	v_pk_fma_f32 v[144:145], v[24:25], v[196:197], v[136:137] op_sel_hi:[1,0,1]
	global_store_dwordx4 v[148:149], v[144:147], off offset:16
	s_nop 1
	v_pk_fma_f32 v[146:147], v[22:23], v[196:197], v[134:135] op_sel_hi:[1,0,1]
	v_pk_fma_f32 v[144:145], v[20:21], v[196:197], v[132:133] op_sel_hi:[1,0,1]
	global_store_dwordx4 v[148:149], v[144:147], off offset:512
	s_nop 1
	v_pk_fma_f32 v[146:147], v[18:19], v[196:197], v[130:131] op_sel_hi:[1,0,1]
	v_pk_fma_f32 v[144:145], v[16:17], v[196:197], v[128:129] op_sel_hi:[1,0,1]
	global_store_dwordx4 v[148:149], v[144:147], off offset:528
	s_and_saveexec_b64 s[4:5], vcc
	s_xor_b64 s[4:5], exec, s[4:5]
	s_movk_i32 s6, 0xc4b0
	s_mov_b32 s7, -1
	v_lshl_add_u64 v[144:145], v[224:225], 0, s[6:7]
	s_or_saveexec_b64 s[4:5], s[4:5]
	v_mov_b64_e32 v[146:147], 0x2ae6000
	s_xor_b64 exec, exec, s[4:5]
	v_add_u32_e32 v144, 0xb0, v224
	v_ashrrev_i32_e32 v145, 31, v144
	s_mov_b64 s[6:7], 0x4000
	v_lshl_add_u64 v[144:145], v[144:145], 0, s[6:7]
	v_mov_b64_e32 v[146:147], 0x1a00000
	s_or_b64 exec, exec, s[4:5]
	v_lshlrev_b32_e32 v224, 2, v146
	v_lshl_add_u64 v[146:147], s[84:85], 0, v[224:225]
	v_lshlrev_b64 v[144:145], 10, v[144:145]
	v_lshl_add_u64 v[144:145], v[146:147], 0, v[144:145]
	v_lshl_add_u64 v[144:145], v[198:199], 2, v[144:145]
	v_pk_fma_f32 v[142:143], v[14:15], v[194:195], v[142:143] op_sel_hi:[1,0,1]
	v_pk_fma_f32 v[140:141], v[12:13], v[194:195], v[140:141] op_sel_hi:[1,0,1]
	v_pk_fma_f32 v[138:139], v[10:11], v[194:195], v[138:139] op_sel_hi:[1,0,1]
	v_pk_fma_f32 v[136:137], v[8:9], v[194:195], v[136:137] op_sel_hi:[1,0,1]
	v_pk_fma_f32 v[134:135], v[6:7], v[194:195], v[134:135] op_sel_hi:[1,0,1]
	v_pk_fma_f32 v[132:133], v[4:5], v[194:195], v[132:133] op_sel_hi:[1,0,1]
	v_pk_fma_f32 v[130:131], v[2:3], v[194:195], v[130:131] op_sel_hi:[1,0,1]
	v_pk_fma_f32 v[128:129], v[0:1], v[194:195], v[128:129] op_sel_hi:[1,0,1]
	s_mov_b64 s[80:81], 0
	global_store_dwordx4 v[144:145], v[140:143], off
	global_store_dwordx4 v[144:145], v[136:139], off offset:16
	global_store_dwordx4 v[144:145], v[132:135], off offset:512
	global_store_dwordx4 v[144:145], v[128:131], off offset:528

; DI float sum16(const float* p) { const f32x4* q = (const f32x4*)p; f32x4 a = q[0], b = q[1], c = q[2], d = q[3]; f32x4 s = (a + b) + (c + d); return (s[0] + s[1]) + (s[2] + s[3]); }
;     template <int PN> DI void body(AccRef acc, const Unit& u, int wr, int wc, int fr, int fq) const {
;     ...
;         for (int ai = 0; ai < 2; ++ai) {
;             const int rb_ = u.pm * 256 + ai * 128 + wr * 64 + fr;
; #pragma unroll
;             for (int m = 0; m < 4; ++m) rinvh[ai][m] = rsqrtf(sum16(ssq + (size_t)(rb_ + 16 * m + zdep) * 16) * (1.f / 1024.f) + EPS);
;             asm volatile("v_mov_b32 %0, 0" : "=v"(zdep) : "v"(rinvh[ai][0]), "v"(rinvh[ai][1]), "v"(rinvh[ai][2]), "v"(rinvh[ai][3]));
;         }
;     DI void operator()(AccRef acc, const Unit& u, int wr, int wc, int fr, int fq) const {
;         switch (u.pn) {
;             case 0: body<0>(acc, u, wr, wc, fr, fq); break;
;             case 1: body<1>(acc, u, wr, wc, fr, fq); break;
;             case 2: body<2>(acc, u, wr, wc, fr, fq); break;
;             case 3: body<3>(acc, u, wr, wc, fr, fq); break;
;             case 4: body<4>(acc, u, wr, wc, fr, fq); break;
;             case 5: body<5>(acc, u, wr, wc, fr, fq); break;
;             case 6: body<6>(acc, u, wr, wc, fr, fq); break;
;             case 7: body<7>(acc, u, wr, wc, fr, fq); break;
;             case 8: body<8>(acc, u, wr, wc, fr, fq); break;
;             default: body<9>(acc, u, wr, wc, fr, fq); break;
.LBB0_1878:
	v_readlane_b32 s2, v253, 32
	v_mbcnt_lo_u32_b32 v128, -1, 0
	v_mbcnt_hi_u32_b32 v128, -1, v128
	s_mov_b32 s60, s39
	v_and_b32_e32 v214, 15, v128
	v_bfe_u32 v213, v128, 4, 2
	s_lshl_b32 s98, s29, 6
	s_lshl_b32 s99, s34, 8
	s_add_i32 s98, s98, s99
	v_add_u32_e32 v248, s98, v214
	v_lshlrev_b32_e32 v248, 6, v248
	v_lshl_add_u32 v248, v213, 4, v248
	global_load_dwordx4 v[244:247], v248, s[70:71]
	global_load_dwordx4 v[244:247], v248, s[70:71] offset:1024
	global_load_dwordx4 v[244:247], v248, s[70:71] offset:2048
	global_load_dwordx4 v[244:247], v248, s[70:71] offset:3072
	v_add_u32_e32 v248, 0x2000, v248
	global_load_dwordx4 v[244:247], v248, s[70:71]
	global_load_dwordx4 v[244:247], v248, s[70:71] offset:1024
	global_load_dwordx4 v[244:247], v248, s[70:71] offset:2048
	global_load_dwordx4 v[244:247], v248, s[70:71] offset:3072
	s_mov_b32 s43, s29
	s_mov_b64 s[2:3], -1
	s_mov_b64 s[8:9], 0
	s_cmp_lt_i32 s66, 4
	s_mov_b64 s[80:81], 0
	s_cbranch_scc1 .LBB0_1913
	s_cmp_gt_i32 s66, 5
	s_cbranch_scc0 .LBB0_1907
	s_cmp_gt_i32 s66, 6
	s_cbranch_scc0 .LBB0_1904
	s_cmp_gt_i32 s66, 7
	s_cbranch_scc0 .LBB0_1901
	s_cmp_eq_u32 s66, 8
	s_mov_b64 s[80:81], -1
	s_cbranch_scc0 .LBB0_1900
	s_lshl_b32 s2, s43, 6
	s_lshl_b32 s3, s34, 8
	s_add_i32 s2, s2, s3
	v_add_u32_e32 v160, s2, v214
	v_ashrrev_i32_e32 v161, 31, v160
	v_lshlrev_b64 v[128:129], 6, v[160:161]
	v_lshl_add_u64 v[140:141], s[70:71], 0, v[128:129]
	global_load_dwordx4 v[128:131], v[140:141], off offset:32
	global_load_dwordx4 v[132:135], v[140:141], off offset:48
	global_load_dwordx4 v[136:139], v[140:141], off
	s_nop 0
	global_load_dwordx4 v[140:143], v[140:141], off offset:16
	v_add_u32_e32 v190, 16, v160
	v_ashrrev_i32_e32 v191, 31, v190
	s_mov_b32 s2, 0x358637bd
	s_mov_b32 s4, 0x3a800000
	v_add_u32_e32 v166, 32, v160
	v_ashrrev_i32_e32 v167, 31, v166
	v_add_u32_e32 v168, 48, v160
	v_ashrrev_i32_e32 v169, 31, v168
	v_add_u32_e32 v164, 0x80, v160
	s_movk_i32 s6, 0x2800
	s_mov_b64 s[12:13], 0x126000
	s_mov_b32 s7, 0x126000
	v_add_u32_e32 v163, 0xffffc080, v160
	v_mov_b32_e32 v165, 0xffffc400
	v_mov_b32_e32 v171, 0x4000
	s_waitcnt vmcnt(0)
	v_pk_add_f32 v[130:131], v[130:131], v[134:135]
	v_pk_add_f32 v[128:129], v[128:129], v[132:133]
	v_pk_add_f32 v[138:139], v[138:139], v[142:143]
	v_pk_add_f32 v[136:137], v[136:137], v[140:141]
	v_pk_add_f32 v[130:131], v[138:139], v[130:131]
	v_pk_add_f32 v[128:129], v[136:137], v[128:129]
	s_nop 0
	v_pk_mov_b32 v[132:133], v[128:129], v[130:131] op_sel:[1,0]
	v_mov_b32_e32 v129, v131
	v_pk_add_f32 v[144:145], v[132:133], v[128:129]
	v_lshlrev_b64 v[128:129], 6, v[190:191]
	v_lshl_add_u64 v[140:141], s[70:71], 0, v[128:129]
	global_load_dwordx4 v[128:131], v[140:141], off offset:32
	global_load_dwordx4 v[132:135], v[140:141], off offset:48
	global_load_dwordx4 v[136:139], v[140:141], off
	s_nop 0
	global_load_dwordx4 v[140:143], v[140:141], off offset:16
	s_waitcnt vmcnt(2)
	v_pk_add_f32 v[130:131], v[130:131], v[134:135]
	v_pk_add_f32 v[128:129], v[128:129], v[132:133]
	s_waitcnt vmcnt(0)
	v_pk_add_f32 v[138:139], v[138:139], v[142:143]
	v_pk_add_f32 v[136:137], v[136:137], v[140:141]
	v_pk_add_f32 v[130:131], v[138:139], v[130:131]
	v_pk_add_f32 v[128:129], v[136:137], v[128:129]
	s_nop 0
	v_pk_mov_b32 v[132:133], v[128:129], v[130:131] op_sel:[1,0]
	v_mov_b32_e32 v129, v131
	v_pk_add_f32 v[128:129], v[132:133], v[128:129]
	v_mov_b32_e32 v131, v144
	v_mov_b32_e32 v130, v128
	v_mov_b32_e32 v144, v129
	v_pk_add_f32 v[130:131], v[130:131], v[144:145]
	v_mov_b64_e32 v[128:129], s[2:3]
	v_pk_fma_f32 v[130:131], v[130:131], s[4:5], v[128:129] op_sel_hi:[1,0,0]
	s_nop 0
	v_mul_f32_e32 v132, 0x4b800000, v131
	v_cmp_gt_f32_e64 s[2:3], s33, v131
	v_cmp_gt_f32_e32 vcc, s33, v130
	s_nop 0
	v_cndmask_b32_e64 v131, v131, v132, s[2:3]
	v_rsq_f32_e32 v131, v131
	s_nop 0
	v_mul_f32_e32 v132, 0x45800000, v131
	v_cndmask_b32_e64 v192, v131, v132, s[2:3]
	v_mul_f32_e32 v131, 0x4b800000, v130
	v_cndmask_b32_e32 v130, v130, v131, vcc
	v_rsq_f32_e32 v130, v130
	s_nop 0
	v_mul_f32_e32 v131, 0x45800000, v130
	v_cndmask_b32_e32 v162, v130, v131, vcc
	v_lshlrev_b64 v[130:131], 6, v[166:167]
	v_lshl_add_u64 v[142:143], s[70:71], 0, v[130:131]
	global_load_dwordx4 v[130:133], v[142:143], off offset:32
	global_load_dwordx4 v[134:137], v[142:143], off offset:48
	global_load_dwordx4 v[138:141], v[142:143], off
	s_nop 0
	global_load_dwordx4 v[142:145], v[142:143], off offset:16
	s_waitcnt vmcnt(2)
	v_pk_add_f32 v[132:133], v[132:133], v[136:137]
	v_pk_add_f32 v[130:131], v[130:131], v[134:135]
	s_waitcnt vmcnt(0)
	v_pk_add_f32 v[140:141], v[140:141], v[144:145]
	v_pk_add_f32 v[138:139], v[138:139], v[142:143]
	v_pk_add_f32 v[132:133], v[140:141], v[132:133]
	v_pk_add_f32 v[130:131], v[138:139], v[130:131]
	s_nop 0
	v_pk_mov_b32 v[134:135], v[130:131], v[132:133] op_sel:[1,0]
	v_mov_b32_e32 v131, v133
	v_pk_add_f32 v[146:147], v[134:135], v[130:131]
	v_lshlrev_b64 v[130:131], 6, v[168:169]
	v_lshl_add_u64 v[142:143], s[70:71], 0, v[130:131]
	global_load_dwordx4 v[130:133], v[142:143], off offset:32
	global_load_dwordx4 v[134:137], v[142:143], off offset:48
	global_load_dwordx4 v[138:141], v[142:143], off
	s_nop 0
	global_load_dwordx4 v[142:145], v[142:143], off offset:16
	s_waitcnt vmcnt(2)
	v_pk_add_f32 v[132:133], v[132:133], v[136:137]
	v_pk_add_f32 v[130:131], v[130:131], v[134:135]
	s_waitcnt vmcnt(0)
; DI float sum16(const float* p) { const f32x4* q = (const f32x4*)p; f32x4 a = q[0], b = q[1], c = q[2], d = q[3]; f32x4 s = (a + b) + (c + d); return (s[0] + s[1]) + (s[2] + s[3]); }
;     template <int PN> DI void body(AccRef acc, const Unit& u, int wr, int wc, int fr, int fq) const {
;     ...
;         for (int ai = 0; ai < 2; ++ai) {
;             const int rb_ = u.pm * 256 + ai * 128 + wr * 64 + fr;
; #pragma unroll
;             for (int m = 0; m < 4; ++m) rinvh[ai][m] = rsqrtf(sum16(ssq + (size_t)(rb_ + 16 * m + zdep) * 16) * (1.f / 1024.f) + EPS);
;             asm volatile("v_mov_b32 %0, 0" : "=v"(zdep) : "v"(rinvh[ai][0]), "v"(rinvh[ai][1]), "v"(rinvh[ai][2]), "v"(rinvh[ai][3]));
;         }
	v_pk_add_f32 v[140:141], v[140:141], v[144:145]
	v_pk_add_f32 v[138:139], v[138:139], v[142:143]
	v_pk_add_f32 v[132:133], v[140:141], v[132:133]
	v_pk_add_f32 v[130:131], v[138:139], v[130:131]
	s_nop 0
	v_pk_mov_b32 v[134:135], v[130:131], v[132:133] op_sel:[1,0]
	v_mov_b32_e32 v131, v133
	v_pk_add_f32 v[130:131], v[134:135], v[130:131]
	v_mov_b32_e32 v133, v146
	v_mov_b32_e32 v132, v130
	v_mov_b32_e32 v146, v131
	v_pk_add_f32 v[130:131], v[132:133], v[146:147]
	s_nop 0
	v_pk_fma_f32 v[130:131], v[130:131], s[4:5], v[128:129] op_sel_hi:[1,0,0]
	s_nop 0
	v_mul_f32_e32 v132, 0x4b800000, v131
	v_cmp_gt_f32_e64 s[2:3], s33, v131
	v_cmp_gt_f32_e32 vcc, s33, v130
	s_nop 0
	v_cndmask_b32_e64 v131, v131, v132, s[2:3]
	v_rsq_f32_e32 v131, v131
	s_nop 0
	v_mul_f32_e32 v132, 0x45800000, v131
	v_cndmask_b32_e64 v172, v131, v132, s[2:3]
	v_mul_f32_e32 v131, 0x4b800000, v130
	v_cndmask_b32_e32 v130, v130, v131, vcc
	v_rsq_f32_e32 v130, v130
	s_nop 0
	v_mul_f32_e32 v131, 0x45800000, v130
	v_cndmask_b32_e32 v188, v130, v131, vcc
	v_mov_b32 v130, 0
	s_nop 0
	v_add_u32_e32 v130, v130, v164
	v_ashrrev_i32_e32 v131, 31, v130
	v_lshlrev_b64 v[132:133], 6, v[130:131]
	v_lshl_add_u64 v[144:145], s[70:71], 0, v[132:133]
	global_load_dwordx4 v[132:135], v[144:145], off offset:32
	global_load_dwordx4 v[136:139], v[144:145], off offset:48
	global_load_dwordx4 v[140:143], v[144:145], off
	s_nop 0
	global_load_dwordx4 v[144:147], v[144:145], off offset:16
	s_waitcnt vmcnt(2)
	v_pk_add_f32 v[134:135], v[134:135], v[138:139]
	v_pk_add_f32 v[132:133], v[132:133], v[136:137]
	s_waitcnt vmcnt(0)
	v_pk_add_f32 v[142:143], v[142:143], v[146:147]
	v_pk_add_f32 v[140:141], v[140:141], v[144:145]
	v_pk_add_f32 v[134:135], v[142:143], v[134:135]
	v_pk_add_f32 v[132:133], v[140:141], v[132:133]
	s_nop 0
	v_pk_mov_b32 v[136:137], v[132:133], v[134:135] op_sel:[1,0]
	v_mov_b32_e32 v133, v135
	v_pk_add_f32 v[148:149], v[136:137], v[132:133]
	v_add_u32_e32 v132, 16, v130
	v_ashrrev_i32_e32 v133, 31, v132
	v_lshlrev_b64 v[132:133], 6, v[132:133]
	v_lshl_add_u64 v[144:145], s[70:71], 0, v[132:133]
	global_load_dwordx4 v[132:135], v[144:145], off offset:32
	global_load_dwordx4 v[136:139], v[144:145], off offset:48
	global_load_dwordx4 v[140:143], v[144:145], off
	s_nop 0
	global_load_dwordx4 v[144:147], v[144:145], off offset:16
	s_waitcnt vmcnt(2)
	v_pk_add_f32 v[134:135], v[134:135], v[138:139]
	v_pk_add_f32 v[132:133], v[132:133], v[136:137]
	s_waitcnt vmcnt(0)
	v_pk_add_f32 v[142:143], v[142:143], v[146:147]
	v_pk_add_f32 v[140:141], v[140:141], v[144:145]
	v_pk_add_f32 v[134:135], v[142:143], v[134:135]
	v_pk_add_f32 v[132:133], v[140:141], v[132:133]
	s_nop 0
	v_pk_mov_b32 v[136:137], v[132:133], v[134:135] op_sel:[1,0]
	v_mov_b32_e32 v133, v135
	v_pk_add_f32 v[132:133], v[136:137], v[132:133]
	v_mov_b32_e32 v135, v148
	v_mov_b32_e32 v134, v132
	v_mov_b32_e32 v148, v133
	v_pk_add_f32 v[132:133], v[134:135], v[148:149]
	s_nop 0
	v_pk_fma_f32 v[132:133], v[132:133], s[4:5], v[128:129] op_sel_hi:[1,0,0]
	s_nop 0
	v_mul_f32_e32 v131, 0x4b800000, v133
	v_cmp_gt_f32_e64 s[2:3], s33, v133
	v_cmp_gt_f32_e32 vcc, s33, v132
	s_nop 0
	v_cndmask_b32_e64 v131, v133, v131, s[2:3]
	v_rsq_f32_e32 v131, v131
	s_nop 0
	v_mul_f32_e32 v133, 0x45800000, v131
	v_cndmask_b32_e64 v174, v131, v133, s[2:3]
	v_mul_f32_e32 v131, 0x4b800000, v132
	v_cndmask_b32_e32 v131, v132, v131, vcc
	v_rsq_f32_e32 v131, v131
	s_nop 0
	v_mul_f32_e32 v132, 0x45800000, v131
	v_cndmask_b32_e32 v170, v131, v132, vcc
	v_add_u32_e32 v132, 32, v130
	v_ashrrev_i32_e32 v133, 31, v132
	v_lshlrev_b64 v[132:133], 6, v[132:133]
	v_lshl_add_u64 v[144:145], s[70:71], 0, v[132:133]
	global_load_dwordx4 v[132:135], v[144:145], off offset:32
	global_load_dwordx4 v[136:139], v[144:145], off offset:48
	global_load_dwordx4 v[140:143], v[144:145], off
	s_nop 0
	global_load_dwordx4 v[144:147], v[144:145], off offset:16
	v_add_u32_e32 v130, 48, v130
	v_ashrrev_i32_e32 v131, 31, v130
	v_lshlrev_b64 v[130:131], 6, v[130:131]
	s_waitcnt vmcnt(2)
	v_pk_add_f32 v[134:135], v[134:135], v[138:139]
	v_pk_add_f32 v[132:133], v[132:133], v[136:137]
	s_waitcnt vmcnt(0)
	v_pk_add_f32 v[142:143], v[142:143], v[146:147]
	v_pk_add_f32 v[140:141], v[140:141], v[144:145]
	v_pk_add_f32 v[134:135], v[142:143], v[134:135]
	v_pk_add_f32 v[132:133], v[140:141], v[132:133]
	v_lshl_add_u64 v[142:143], s[70:71], 0, v[130:131]
	v_pk_mov_b32 v[136:137], v[132:133], v[134:135] op_sel:[1,0]
	v_mov_b32_e32 v133, v135
	v_pk_add_f32 v[146:147], v[136:137], v[132:133]
	global_load_dwordx4 v[130:133], v[142:143], off offset:32
	global_load_dwordx4 v[134:137], v[142:143], off offset:48
	global_load_dwordx4 v[138:141], v[142:143], off
	s_nop 0
	global_load_dwordx4 v[142:145], v[142:143], off offset:16
	s_waitcnt vmcnt(2)
	v_pk_add_f32 v[132:133], v[132:133], v[136:137]
	v_pk_add_f32 v[130:131], v[130:131], v[134:135]
	s_waitcnt vmcnt(0)
;     template <int PN> DI void body(AccRef acc, const Unit& u, int wr, int wc, int fr, int fq) const {
;     ...
; #pragma unroll
;         for (int ai = 0; ai < 2; ++ai) {
;             const int rb_ = u.pm * 256 + ai * 128 + wr * 64 + fr;
;             int mb_, p_, k_; row_info(rb_, mb_, p_, k_);
; #pragma unroll
;             for (int bj = 0; bj < 2; ++bj)
; #pragma unroll
;                 for (int n = 0; n < 2; ++n) cvh[ai][bj][n] = *(const f32x4*)(cv + (size_t)(mb_ + zdep) * NIN + PN * 256 + bj * 128 + cl + 4 * n);
;         }
;     ...
;                     float* lo = orow(out, l, row, PN == 8 ? O_PSK : O_PSV, PN == 8 ? O_SSK : O_SSV, 256);
; #pragma unroll
;                     for (int bj = 0; bj < 2; ++bj) {
;                         *(f32x4*)(lo + bj * 128 + cl) = (f32x4){v[bj][0], v[bj][1], v[bj][2], v[bj][3]};
;                         *(f32x4*)(lo + bj * 128 + cl + 4) = (f32x4){v[bj][4], v[bj][5], v[bj][6], v[bj][7]};
;                     }
	v_pk_add_f32 v[140:141], v[140:141], v[144:145]
	v_pk_add_f32 v[138:139], v[138:139], v[142:143]
	v_pk_add_f32 v[132:133], v[140:141], v[132:133]
	v_pk_add_f32 v[130:131], v[138:139], v[130:131]
	s_nop 0
	v_pk_mov_b32 v[134:135], v[130:131], v[132:133] op_sel:[1,0]
	v_mov_b32_e32 v131, v133
	v_pk_add_f32 v[130:131], v[134:135], v[130:131]
	v_mov_b32_e32 v133, v146
	v_mov_b32_e32 v132, v130
	v_mov_b32_e32 v146, v131
	v_pk_add_f32 v[130:131], v[132:133], v[146:147]
	s_nop 0
	v_pk_fma_f32 v[128:129], v[130:131], s[4:5], v[128:129] op_sel_hi:[1,0,0]
	s_nop 0
	v_mul_f32_e32 v130, 0x4b800000, v129
	v_cmp_gt_f32_e64 s[2:3], s33, v129
	v_cmp_gt_f32_e32 vcc, s33, v128
	s_nop 0
	v_cndmask_b32_e64 v129, v129, v130, s[2:3]
	v_rsq_f32_e32 v129, v129
	s_nop 0
	v_mul_f32_e32 v130, 0x45800000, v129
	v_cndmask_b32_e64 v196, v129, v130, s[2:3]
	v_mul_f32_e32 v129, 0x4b800000, v128
	v_cndmask_b32_e32 v128, v128, v129, vcc
	v_rsq_f32_e32 v128, v128
	s_lshl_b32 s2, s60, 5
	v_lshl_add_u32 v198, v213, 3, s2
	v_cmp_gt_i32_e64 s[2:3], s94, v160
	v_mul_f32_e32 v129, 0x45800000, v128
	v_cndmask_b32_e32 v194, v128, v129, vcc
	v_add_u32_e32 v129, 0xffffc000, v160
	v_lshrrev_b32_e32 v129, 6, v129
	v_ashrrev_i32_e32 v128, 11, v160
	v_add_u32_e32 v129, 8, v129
	v_cndmask_b32_e64 v128, v129, v128, s[2:3]
	v_mov_b32 v134, 0
	v_ashrrev_i32_e32 v199, 31, v198
	v_add_u32_e32 v130, v134, v128
	v_mov_b64_e32 v[128:129], s[74:75]
	v_mad_i64_i32 v[130:131], s[4:5], v130, s6, v[128:129]
	v_lshlrev_b64 v[200:201], 2, v[198:199]
	v_lshl_add_u64 v[130:131], v[130:131], 0, v[200:201]
	v_lshl_add_u64 v[132:133], v[130:131], 0, s[12:13]
	v_add_co_u32_e32 v130, vcc, s7, v130
	s_movk_i32 s4, 0x3fff
	s_nop 0
	v_addc_co_u32_e32 v131, vcc, 0, v131, vcc
	global_load_dwordx4 v[152:155], v[130:131], off
	global_load_dwordx4 v[156:159], v[132:133], off offset:16
	global_load_dwordx4 v[144:147], v[132:133], off offset:528
	global_load_dwordx4 v[148:151], v[132:133], off offset:512
	v_lshrrev_b32_e32 v131, 6, v163
	v_cmp_lt_i32_e32 vcc, s4, v164
	v_cmp_gt_i32_e64 s[4:5], s94, v164
	v_ashrrev_i32_e32 v130, 11, v164
	v_add_u32_e32 v131, 8, v131
	v_cndmask_b32_e64 v130, v131, v130, s[4:5]
	v_add_u32_e32 v130, v134, v130
	v_mad_i64_i32 v[128:129], s[4:5], v130, s6, v[128:129]
	v_lshl_add_u64 v[128:129], v[128:129], 0, v[200:201]
	v_lshl_add_u64 v[132:133], v[128:129], 0, s[12:13]
	v_add_co_u32_e64 v128, s[4:5], s7, v128
	v_cndmask_b32_e64 v203, -1, 0, s[2:3]
	s_nop 0
	v_addc_co_u32_e64 v129, s[4:5], 0, v129, s[4:5]
	global_load_dwordx4 v[140:143], v[128:129], off
	global_load_dwordx4 v[136:139], v[132:133], off offset:16
	s_nop 0
	global_load_dwordx4 v[128:131], v[132:133], off offset:528
	s_nop 0
	global_load_dwordx4 v[132:135], v[132:133], off offset:512
	v_cndmask_b32_e64 v202, v165, v171, s[2:3]
	v_mov_b32_e32 v165, 0xab98000
	v_mov_b32_e32 v171, 0x6800000
	v_lshl_add_u64 v[202:203], v[202:203], 0, v[160:161]
	v_cndmask_b32_e64 v224, v165, v171, s[2:3]
	v_lshl_add_u64 v[204:205], s[84:85], 0, v[224:225]
	v_lshlrev_b64 v[202:203], 10, v[202:203]
	v_lshl_add_u64 v[202:203], v[204:205], 0, v[202:203]
	v_lshl_add_u64 v[206:207], v[202:203], 0, v[200:201]
	s_movk_i32 s4, 0xc410
	v_mov_b32_e32 v224, v160
	s_mov_b32 s5, -1
	v_cmp_gt_i32_e64 s[2:3], s82, v160
	s_movk_i32 s6, 0xc420
	s_mov_b32 s7, -1
	s_waitcnt vmcnt(7)
	v_pk_fma_f32 v[204:205], v[126:127], v[192:193], v[154:155] op_sel_hi:[1,0,1]
	v_pk_fma_f32 v[202:203], v[124:125], v[192:193], v[152:153] op_sel_hi:[1,0,1]
	global_store_dwordx4 v[206:207], v[202:205], off
	s_waitcnt vmcnt(7)
	s_nop 0
	v_pk_fma_f32 v[204:205], v[122:123], v[192:193], v[158:159] op_sel_hi:[1,0,1]
	v_pk_fma_f32 v[202:203], v[120:121], v[192:193], v[156:157] op_sel_hi:[1,0,1]
	global_store_dwordx4 v[206:207], v[202:205], off offset:16
	s_waitcnt vmcnt(6)
	s_nop 0
	v_pk_fma_f32 v[204:205], v[118:119], v[192:193], v[150:151] op_sel_hi:[1,0,1]
	v_pk_fma_f32 v[202:203], v[116:117], v[192:193], v[148:149] op_sel_hi:[1,0,1]
	global_store_dwordx4 v[206:207], v[202:205], off offset:512
	s_nop 1
	v_pk_fma_f32 v[204:205], v[114:115], v[192:193], v[146:147] op_sel_hi:[1,0,1]
	v_pk_fma_f32 v[202:203], v[112:113], v[192:193], v[144:145] op_sel_hi:[1,0,1]
	v_lshl_add_u64 v[192:193], v[224:225], 0, s[4:5]
	s_mov_b64 s[4:5], 0x4000
	v_lshl_add_u64 v[190:191], v[190:191], 0, s[4:5]
	v_cndmask_b32_e64 v191, v193, v191, s[2:3]
	v_cndmask_b32_e64 v190, v192, v190, s[2:3]
	v_cndmask_b32_e64 v192, v165, v171, s[2:3]
	v_mov_b32_e32 v193, v225
	v_lshl_add_u64 v[192:193], s[84:85], 0, v[192:193]
	v_lshlrev_b64 v[190:191], 10, v[190:191]
	v_lshl_add_u64 v[190:191], v[192:193], 0, v[190:191]
	global_store_dwordx4 v[206:207], v[202:205], off offset:528
	v_pk_fma_f32 v[192:193], v[110:111], v[162:163], v[154:155] op_sel_hi:[1,0,1]
	v_cmp_gt_i32_e64 s[2:3], s83, v160
	v_lshl_add_u64 v[202:203], v[190:191], 0, v[200:201]
	v_pk_fma_f32 v[190:191], v[108:109], v[162:163], v[152:153] op_sel_hi:[1,0,1]
	global_store_dwordx4 v[202:203], v[190:193], off
	v_lshl_add_u64 v[166:167], v[166:167], 0, s[4:5]
	s_nop 0
	v_pk_fma_f32 v[192:193], v[106:107], v[162:163], v[158:159] op_sel_hi:[1,0,1]
	v_pk_fma_f32 v[190:191], v[104:105], v[162:163], v[156:157] op_sel_hi:[1,0,1]
	global_store_dwordx4 v[202:203], v[190:193], off offset:16
	s_nop 1
	v_pk_fma_f32 v[192:193], v[102:103], v[162:163], v[150:151] op_sel_hi:[1,0,1]
	v_pk_fma_f32 v[190:191], v[100:101], v[162:163], v[148:149] op_sel_hi:[1,0,1]
	global_store_dwordx4 v[202:203], v[190:193], off offset:512
	s_nop 1
	v_pk_fma_f32 v[192:193], v[98:99], v[162:163], v[146:147] op_sel_hi:[1,0,1]
	v_pk_fma_f32 v[190:191], v[96:97], v[162:163], v[144:145] op_sel_hi:[1,0,1]
;     template <int PN> DI void body(AccRef acc, const Unit& u, int wr, int wc, int fr, int fq) const {
;     ...
;                     float* lo = orow(out, l, row, PN == 8 ? O_PSK : O_PSV, PN == 8 ? O_SSK : O_SSV, 256);
; #pragma unroll
;                     for (int bj = 0; bj < 2; ++bj) {
;                         *(f32x4*)(lo + bj * 128 + cl) = (f32x4){v[bj][0], v[bj][1], v[bj][2], v[bj][3]};
;                         *(f32x4*)(lo + bj * 128 + cl + 4) = (f32x4){v[bj][4], v[bj][5], v[bj][6], v[bj][7]};
;                     }
	global_store_dwordx4 v[202:203], v[190:193], off offset:528
	s_nop 1
	v_lshl_add_u64 v[190:191], v[224:225], 0, s[6:7]
	v_cndmask_b32_e64 v167, v191, v167, s[2:3]
	v_cndmask_b32_e64 v166, v190, v166, s[2:3]
	v_cndmask_b32_e64 v190, v165, v171, s[2:3]
	v_mov_b32_e32 v191, v225
	v_lshl_add_u64 v[190:191], s[84:85], 0, v[190:191]
	v_lshlrev_b64 v[166:167], 10, v[166:167]
	v_lshl_add_u64 v[166:167], v[190:191], 0, v[166:167]
	v_lshl_add_u64 v[166:167], v[166:167], 0, v[200:201]
	v_pk_fma_f32 v[192:193], v[94:95], v[172:173], v[154:155] op_sel_hi:[1,0,1]
	v_pk_fma_f32 v[190:191], v[92:93], v[172:173], v[152:153] op_sel_hi:[1,0,1]
	global_store_dwordx4 v[166:167], v[190:193], off
	s_movk_i32 s6, 0xc430
	s_mov_b32 s7, -1
	v_pk_fma_f32 v[192:193], v[90:91], v[172:173], v[158:159] op_sel_hi:[1,0,1]
	v_pk_fma_f32 v[190:191], v[88:89], v[172:173], v[156:157] op_sel_hi:[1,0,1]
	global_store_dwordx4 v[166:167], v[190:193], off offset:16
	v_cmp_gt_i32_e64 s[2:3], s92, v160
	v_lshl_add_u64 v[160:161], v[224:225], 0, s[6:7]
	v_pk_fma_f32 v[192:193], v[86:87], v[172:173], v[150:151] op_sel_hi:[1,0,1]
	v_pk_fma_f32 v[190:191], v[84:85], v[172:173], v[148:149] op_sel_hi:[1,0,1]
	global_store_dwordx4 v[166:167], v[190:193], off offset:512
	v_pk_fma_f32 v[154:155], v[78:79], v[188:189], v[154:155] op_sel_hi:[1,0,1]
	v_pk_fma_f32 v[152:153], v[76:77], v[188:189], v[152:153] op_sel_hi:[1,0,1]
	v_pk_fma_f32 v[192:193], v[82:83], v[172:173], v[146:147] op_sel_hi:[1,0,1]
	v_pk_fma_f32 v[190:191], v[80:81], v[172:173], v[144:145] op_sel_hi:[1,0,1]
	global_store_dwordx4 v[166:167], v[190:193], off offset:528
	v_lshl_add_u64 v[166:167], v[168:169], 0, s[4:5]
	v_cndmask_b32_e64 v161, v161, v167, s[2:3]
	v_cndmask_b32_e64 v160, v160, v166, s[2:3]
	v_cndmask_b32_e64 v166, v165, v171, s[2:3]
	v_mov_b32_e32 v167, v225
	v_lshl_add_u64 v[166:167], s[84:85], 0, v[166:167]
	v_lshlrev_b64 v[160:161], 10, v[160:161]
	v_lshl_add_u64 v[160:161], v[166:167], 0, v[160:161]
	v_lshl_add_u64 v[160:161], v[160:161], 0, v[200:201]
	global_store_dwordx4 v[160:161], v[152:155], off
	v_pk_fma_f32 v[150:151], v[70:71], v[188:189], v[150:151] op_sel_hi:[1,0,1]
	v_pk_fma_f32 v[148:149], v[68:69], v[188:189], v[148:149] op_sel_hi:[1,0,1]
	v_pk_fma_f32 v[154:155], v[74:75], v[188:189], v[158:159] op_sel_hi:[1,0,1]
	v_pk_fma_f32 v[152:153], v[72:73], v[188:189], v[156:157] op_sel_hi:[1,0,1]
	v_pk_fma_f32 v[146:147], v[66:67], v[188:189], v[146:147] op_sel_hi:[1,0,1]
	v_pk_fma_f32 v[144:145], v[64:65], v[188:189], v[144:145] op_sel_hi:[1,0,1]
	global_store_dwordx4 v[160:161], v[152:155], off offset:16
	global_store_dwordx4 v[160:161], v[148:151], off offset:512
	global_store_dwordx4 v[160:161], v[144:147], off offset:528
	s_and_saveexec_b64 s[2:3], vcc
	s_xor_b64 s[2:3], exec, s[2:3]
	v_add_u32_e32 v144, 0x400, v163
	v_mov_b32_e32 v145, v225
	s_or_saveexec_b64 s[2:3], s[2:3]
	v_mov_b64_e32 v[146:147], 0x2ae6000
	s_xor_b64 exec, exec, s[2:3]
	v_ashrrev_i32_e32 v165, 31, v164
	v_lshl_add_u64 v[144:145], v[164:165], 0, s[4:5]
	v_mov_b64_e32 v[146:147], 0x1a00000
	s_or_b64 exec, exec, s[2:3]
	v_lshlrev_b32_e32 v146, 2, v146
	v_mov_b32_e32 v147, v225
	v_lshl_add_u64 v[146:147], s[84:85], 0, v[146:147]
	v_lshlrev_b64 v[144:145], 10, v[144:145]
	v_lshl_add_u64 v[144:145], v[146:147], 0, v[144:145]
	v_lshl_add_u64 v[148:149], v[198:199], 2, v[144:145]
	s_waitcnt vmcnt(19)
	v_pk_fma_f32 v[146:147], v[62:63], v[174:175], v[142:143] op_sel_hi:[1,0,1]
	v_pk_fma_f32 v[144:145], v[60:61], v[174:175], v[140:141] op_sel_hi:[1,0,1]
	global_store_dwordx4 v[148:149], v[144:147], off
	s_movk_i32 s2, 0x3fef
	v_cmp_lt_i32_e32 vcc, s2, v164
	s_waitcnt vmcnt(19)
	v_pk_fma_f32 v[146:147], v[58:59], v[174:175], v[138:139] op_sel_hi:[1,0,1]
	v_pk_fma_f32 v[144:145], v[56:57], v[174:175], v[136:137] op_sel_hi:[1,0,1]
	global_store_dwordx4 v[148:149], v[144:147], off offset:16
	s_waitcnt vmcnt(18)
;     template <int PN> DI void body(AccRef acc, const Unit& u, int wr, int wc, int fr, int fq) const {
;     ...
;                     float* lo = orow(out, l, row, PN == 8 ? O_PSK : O_PSV, PN == 8 ? O_SSK : O_SSV, 256);
; #pragma unroll
;                     for (int bj = 0; bj < 2; ++bj) {
;                         *(f32x4*)(lo + bj * 128 + cl) = (f32x4){v[bj][0], v[bj][1], v[bj][2], v[bj][3]};
;                         *(f32x4*)(lo + bj * 128 + cl + 4) = (f32x4){v[bj][4], v[bj][5], v[bj][6], v[bj][7]};
;                     }
	s_nop 0
	v_pk_fma_f32 v[146:147], v[54:55], v[174:175], v[134:135] op_sel_hi:[1,0,1]
	v_pk_fma_f32 v[144:145], v[52:53], v[174:175], v[132:133] op_sel_hi:[1,0,1]
	global_store_dwordx4 v[148:149], v[144:147], off offset:512
	s_nop 1
	v_pk_fma_f32 v[146:147], v[50:51], v[174:175], v[130:131] op_sel_hi:[1,0,1]
	v_pk_fma_f32 v[144:145], v[48:49], v[174:175], v[128:129] op_sel_hi:[1,0,1]
	global_store_dwordx4 v[148:149], v[144:147], off offset:528
	s_and_saveexec_b64 s[2:3], vcc
	s_xor_b64 s[2:3], exec, s[2:3]
	s_movk_i32 s4, 0xc490
	s_mov_b32 s5, -1
	v_lshl_add_u64 v[144:145], v[224:225], 0, s[4:5]
	s_or_saveexec_b64 s[2:3], s[2:3]
	v_mov_b64_e32 v[146:147], 0x2ae6000
	s_xor_b64 exec, exec, s[2:3]
	v_add_u32_e32 v144, 0x90, v224
	v_ashrrev_i32_e32 v145, 31, v144
	s_mov_b64 s[4:5], 0x4000
	v_lshl_add_u64 v[144:145], v[144:145], 0, s[4:5]
	v_mov_b64_e32 v[146:147], 0x1a00000
	s_or_b64 exec, exec, s[2:3]
	v_lshlrev_b32_e32 v146, 2, v146
	v_mov_b32_e32 v147, v225
	v_lshl_add_u64 v[146:147], s[84:85], 0, v[146:147]
	v_lshlrev_b64 v[144:145], 10, v[144:145]
	v_lshl_add_u64 v[144:145], v[146:147], 0, v[144:145]
	v_lshl_add_u64 v[148:149], v[198:199], 2, v[144:145]
	v_pk_fma_f32 v[146:147], v[46:47], v[170:171], v[142:143] op_sel_hi:[1,0,1]
	v_pk_fma_f32 v[144:145], v[44:45], v[170:171], v[140:141] op_sel_hi:[1,0,1]
	global_store_dwordx4 v[148:149], v[144:147], off
	s_movk_i32 s2, 0x3fdf
	v_cmp_lt_i32_e32 vcc, s2, v164
	v_pk_fma_f32 v[146:147], v[42:43], v[170:171], v[138:139] op_sel_hi:[1,0,1]
	v_pk_fma_f32 v[144:145], v[40:41], v[170:171], v[136:137] op_sel_hi:[1,0,1]
	global_store_dwordx4 v[148:149], v[144:147], off offset:16
	s_nop 1
	v_pk_fma_f32 v[146:147], v[38:39], v[170:171], v[134:135] op_sel_hi:[1,0,1]
	v_pk_fma_f32 v[144:145], v[36:37], v[170:171], v[132:133] op_sel_hi:[1,0,1]
	global_store_dwordx4 v[148:149], v[144:147], off offset:512
	s_nop 1
	v_pk_fma_f32 v[146:147], v[30:31], v[170:171], v[130:131] op_sel_hi:[1,0,1]
	v_pk_fma_f32 v[144:145], v[28:29], v[170:171], v[128:129] op_sel_hi:[1,0,1]
	global_store_dwordx4 v[148:149], v[144:147], off offset:528
	s_and_saveexec_b64 s[2:3], vcc
	s_xor_b64 s[2:3], exec, s[2:3]
	s_movk_i32 s4, 0xc4a0
	s_mov_b32 s5, -1
	v_lshl_add_u64 v[144:145], v[224:225], 0, s[4:5]
	s_or_saveexec_b64 s[2:3], s[2:3]
	v_mov_b64_e32 v[146:147], 0x2ae6000
	s_xor_b64 exec, exec, s[2:3]
	v_add_u32_e32 v144, 0xa0, v224
	v_ashrrev_i32_e32 v145, 31, v144
	s_mov_b64 s[4:5], 0x4000
	v_lshl_add_u64 v[144:145], v[144:145], 0, s[4:5]
	v_mov_b64_e32 v[146:147], 0x1a00000
	s_or_b64 exec, exec, s[2:3]
	v_lshlrev_b32_e32 v146, 2, v146
	v_mov_b32_e32 v147, v225
	v_lshl_add_u64 v[146:147], s[84:85], 0, v[146:147]
	v_lshlrev_b64 v[144:145], 10, v[144:145]
	v_lshl_add_u64 v[144:145], v[146:147], 0, v[144:145]
	v_lshl_add_u64 v[148:149], v[198:199], 2, v[144:145]
	v_pk_fma_f32 v[146:147], v[34:35], v[196:197], v[142:143] op_sel_hi:[1,0,1]
	v_pk_fma_f32 v[144:145], v[32:33], v[196:197], v[140:141] op_sel_hi:[1,0,1]
	global_store_dwordx4 v[148:149], v[144:147], off
	s_movk_i32 s2, 0x3fcf
	v_cmp_lt_i32_e32 vcc, s2, v164
	v_pk_fma_f32 v[146:147], v[26:27], v[196:197], v[138:139] op_sel_hi:[1,0,1]
	v_pk_fma_f32 v[144:145], v[24:25], v[196:197], v[136:137] op_sel_hi:[1,0,1]
	global_store_dwordx4 v[148:149], v[144:147], off offset:16
	s_nop 1
	v_pk_fma_f32 v[146:147], v[22:23], v[196:197], v[134:135] op_sel_hi:[1,0,1]
	v_pk_fma_f32 v[144:145], v[20:21], v[196:197], v[132:133] op_sel_hi:[1,0,1]
	global_store_dwordx4 v[148:149], v[144:147], off offset:512
	s_nop 1
	v_pk_fma_f32 v[146:147], v[18:19], v[196:197], v[130:131] op_sel_hi:[1,0,1]
	v_pk_fma_f32 v[144:145], v[16:17], v[196:197], v[128:129] op_sel_hi:[1,0,1]
	global_store_dwordx4 v[148:149], v[144:147], off offset:528
	s_and_saveexec_b64 s[2:3], vcc
	s_xor_b64 s[2:3], exec, s[2:3]
	s_movk_i32 s4, 0xc4b0
	s_mov_b32 s5, -1
	v_lshl_add_u64 v[144:145], v[224:225], 0, s[4:5]
	s_or_saveexec_b64 s[2:3], s[2:3]
	v_mov_b64_e32 v[146:147], 0x2ae6000
	s_xor_b64 exec, exec, s[2:3]
	v_add_u32_e32 v144, 0xb0, v224
	v_ashrrev_i32_e32 v145, 31, v144
	s_mov_b64 s[4:5], 0x4000
	v_lshl_add_u64 v[144:145], v[144:145], 0, s[4:5]
	v_mov_b64_e32 v[146:147], 0x1a00000
	s_or_b64 exec, exec, s[2:3]
	v_lshlrev_b32_e32 v224, 2, v146
	v_lshl_add_u64 v[146:147], s[84:85], 0, v[224:225]
	v_lshlrev_b64 v[144:145], 10, v[144:145]
	v_lshl_add_u64 v[144:145], v[146:147], 0, v[144:145]
	v_lshl_add_u64 v[144:145], v[198:199], 2, v[144:145]
	v_pk_fma_f32 v[142:143], v[14:15], v[194:195], v[142:143] op_sel_hi:[1,0,1]
	v_pk_fma_f32 v[140:141], v[12:13], v[194:195], v[140:141] op_sel_hi:[1,0,1]
	v_pk_fma_f32 v[138:139], v[10:11], v[194:195], v[138:139] op_sel_hi:[1,0,1]
	v_pk_fma_f32 v[136:137], v[8:9], v[194:195], v[136:137] op_sel_hi:[1,0,1]
	v_pk_fma_f32 v[134:135], v[6:7], v[194:195], v[134:135] op_sel_hi:[1,0,1]
	v_pk_fma_f32 v[132:133], v[4:5], v[194:195], v[132:133] op_sel_hi:[1,0,1]
	v_pk_fma_f32 v[130:131], v[2:3], v[194:195], v[130:131] op_sel_hi:[1,0,1]
	v_pk_fma_f32 v[128:129], v[0:1], v[194:195], v[128:129] op_sel_hi:[1,0,1]
	s_mov_b64 s[80:81], 0
	global_store_dwordx4 v[144:145], v[140:143], off
	global_store_dwordx4 v[144:145], v[136:139], off offset:16
	global_store_dwordx4 v[144:145], v[132:135], off offset:512
	global_store_dwordx4 v[144:145], v[128:131], off offset:528
